# gmlp pass body rewritten with batched loads; hg_local gate inputs prefetched; gemm_in epilogue hand-written (branch-free proj stores, packed 8-byte transposed U/V stores)
# speedup vs baseline: 1.1789x; 1.0716x over previous
.LBB0_333:
	s_lshl_b32 s1, s0, 7
	s_lshl_b32 s8, s6, 7
	s_sub_u32 s4, s0, 12
	s_cmp_lt_u32 s4, 4
	s_cbranch_scc1 .Lgi_orig
	s_waitcnt vmcnt(0)
	v_readfirstlane_b32 s10, v134
	v_readfirstlane_b32 s11, v135
	s_add_u32 s10, s10, s62
	s_addc_u32 s11, s11, s63
	s_lshl_b32 s4, s6, 20
	s_add_u32 s10, s10, s4
	s_addc_u32 s11, s11, 0
	s_lshl_b32 s4, s0, 9
	s_cmp_lt_u32 s0, 12
	s_cselect_b32 s5, 0, 2048
	s_sub_u32 s4, s4, s5
	s_add_u32 s10, s10, s4
	s_addc_u32 s11, s11, 0
	v_and_b32_e32 v64, 31, v231
	v_bfe_u32 v65, v231, 6, 1
	v_lshl_or_b32 v65, v65, 6, v64
	v_lshlrev_b32_e32 v65, 2, v65
	v_bfe_u32 v64, v231, 5, 1
	v_bfe_u32 v66, v231, 7, 1
	v_lshl_or_b32 v64, v66, 4, v64
	v_lshl_or_b32 v64, v64, 15, v65
	s_mov_b64 s[4:5], s[10:11]
	global_store_dword v64, v48, s[4:5]
	global_store_dword v64, v32, s[4:5] offset:128
	s_add_u32 s4, s10, 0x2000
	s_addc_u32 s5, s11, 0
	global_store_dword v64, v49, s[4:5]
	global_store_dword v64, v33, s[4:5] offset:128
	s_add_u32 s4, s10, 0x4000
	s_addc_u32 s5, s11, 0
	global_store_dword v64, v50, s[4:5]
	global_store_dword v64, v34, s[4:5] offset:128
	s_add_u32 s4, s10, 0x6000
	s_addc_u32 s5, s11, 0
	global_store_dword v64, v51, s[4:5]
	global_store_dword v64, v35, s[4:5] offset:128
	s_add_u32 s4, s10, 0x10000
	s_addc_u32 s5, s11, 0
	global_store_dword v64, v52, s[4:5]
	global_store_dword v64, v36, s[4:5] offset:128
	s_add_u32 s4, s10, 0x12000
	s_addc_u32 s5, s11, 0
	global_store_dword v64, v53, s[4:5]
	global_store_dword v64, v37, s[4:5] offset:128
	s_add_u32 s4, s10, 0x14000
	s_addc_u32 s5, s11, 0
	global_store_dword v64, v54, s[4:5]
	global_store_dword v64, v38, s[4:5] offset:128
	s_add_u32 s4, s10, 0x16000
	s_addc_u32 s5, s11, 0
	global_store_dword v64, v55, s[4:5]
	global_store_dword v64, v39, s[4:5] offset:128
	s_add_u32 s4, s10, 0x20000
	s_addc_u32 s5, s11, 0
	global_store_dword v64, v56, s[4:5]
	global_store_dword v64, v40, s[4:5] offset:128
	s_add_u32 s4, s10, 0x22000
	s_addc_u32 s5, s11, 0
	global_store_dword v64, v57, s[4:5]
	global_store_dword v64, v41, s[4:5] offset:128
	s_add_u32 s4, s10, 0x24000
	s_addc_u32 s5, s11, 0
	global_store_dword v64, v58, s[4:5]
	global_store_dword v64, v42, s[4:5] offset:128
	s_add_u32 s4, s10, 0x26000
	s_addc_u32 s5, s11, 0
	global_store_dword v64, v59, s[4:5]
	global_store_dword v64, v43, s[4:5] offset:128
	s_add_u32 s4, s10, 0x30000
	s_addc_u32 s5, s11, 0
	global_store_dword v64, v60, s[4:5]
	global_store_dword v64, v44, s[4:5] offset:128
	s_add_u32 s4, s10, 0x32000
	s_addc_u32 s5, s11, 0
	global_store_dword v64, v61, s[4:5]
	global_store_dword v64, v45, s[4:5] offset:128
	s_add_u32 s4, s10, 0x34000
	s_addc_u32 s5, s11, 0
	global_store_dword v64, v62, s[4:5]
	global_store_dword v64, v46, s[4:5] offset:128
	s_add_u32 s4, s10, 0x36000
	s_addc_u32 s5, s11, 0
	global_store_dword v64, v63, s[4:5]
	global_store_dword v64, v47, s[4:5] offset:128
	s_add_u32 s4, s10, 0x40000
	s_addc_u32 s5, s11, 0
	global_store_dword v64, v16, s[4:5]
	global_store_dword v64, v0, s[4:5] offset:128
	s_add_u32 s4, s10, 0x42000
	s_addc_u32 s5, s11, 0
	global_store_dword v64, v17, s[4:5]
	global_store_dword v64, v1, s[4:5] offset:128
	s_add_u32 s4, s10, 0x44000
	s_addc_u32 s5, s11, 0
	global_store_dword v64, v18, s[4:5]
	global_store_dword v64, v2, s[4:5] offset:128
	s_add_u32 s4, s10, 0x46000
	s_addc_u32 s5, s11, 0
	global_store_dword v64, v19, s[4:5]
	global_store_dword v64, v3, s[4:5] offset:128
	s_add_u32 s4, s10, 0x50000
	s_addc_u32 s5, s11, 0
	global_store_dword v64, v20, s[4:5]
	global_store_dword v64, v4, s[4:5] offset:128
	s_add_u32 s4, s10, 0x52000
	s_addc_u32 s5, s11, 0
	global_store_dword v64, v21, s[4:5]
	global_store_dword v64, v5, s[4:5] offset:128
	s_add_u32 s4, s10, 0x54000
	s_addc_u32 s5, s11, 0
	global_store_dword v64, v22, s[4:5]
	global_store_dword v64, v6, s[4:5] offset:128
	s_add_u32 s4, s10, 0x56000
	s_addc_u32 s5, s11, 0
	global_store_dword v64, v23, s[4:5]
	global_store_dword v64, v7, s[4:5] offset:128
	s_add_u32 s4, s10, 0x60000
	s_addc_u32 s5, s11, 0
	global_store_dword v64, v24, s[4:5]
	global_store_dword v64, v8, s[4:5] offset:128
	s_add_u32 s4, s10, 0x62000
	s_addc_u32 s5, s11, 0
	global_store_dword v64, v25, s[4:5]
	global_store_dword v64, v9, s[4:5] offset:128
	s_add_u32 s4, s10, 0x64000
	s_addc_u32 s5, s11, 0
	global_store_dword v64, v26, s[4:5]
	global_store_dword v64, v10, s[4:5] offset:128
	s_add_u32 s4, s10, 0x66000
	s_addc_u32 s5, s11, 0
	global_store_dword v64, v27, s[4:5]
	global_store_dword v64, v11, s[4:5] offset:128
	s_add_u32 s4, s10, 0x70000
	s_addc_u32 s5, s11, 0
	global_store_dword v64, v28, s[4:5]
	global_store_dword v64, v12, s[4:5] offset:128
	s_add_u32 s4, s10, 0x72000
	s_addc_u32 s5, s11, 0
	global_store_dword v64, v29, s[4:5]
	global_store_dword v64, v13, s[4:5] offset:128
	s_add_u32 s4, s10, 0x74000
	s_addc_u32 s5, s11, 0
	global_store_dword v64, v30, s[4:5]
	global_store_dword v64, v14, s[4:5] offset:128
	s_add_u32 s4, s10, 0x76000
	s_addc_u32 s5, s11, 0
	global_store_dword v64, v31, s[4:5]
	global_store_dword v64, v15, s[4:5] offset:128
	s_mov_b64 s[2:3], exec
	s_branch .LBB0_316
.Lgi_orig:
	s_waitcnt vmcnt(0)
	v_readfirstlane_b32 s10, v136
	v_readfirstlane_b32 s11, v137
	s_add_u32 s10, s10, s64
	s_addc_u32 s11, s11, s65
	s_lshl_b32 s4, s6, 7
	s_cmp_lt_u32 s6, 32
	s_cbranch_scc0 .Lgi_uv_lat
	s_and_b32 s5, s4, 0xffffff00
	s_movk_i32 s9, 0x100
	s_mov_b32 s3, 10
	s_branch .Lgi_uv_go
.Lgi_uv_lat:
	s_sub_u32 s5, s4, 0x1000
	s_and_b32 s5, s5, 0xfffff800
	s_add_u32 s5, s5, 0x1000
	s_movk_i32 s9, 0x800
	s_mov_b32 s3, 13
.Lgi_uv_go:
	s_sub_u32 s4, s4, s5
	s_sub_u32 s2, s0, 12
	s_lshr_b32 s7, s2, 1
	s_mul_i32 s7, s7, s9
	s_add_u32 s4, s4, s7
	s_lshl_b32 s4, s4, 1
	s_lshl_b32 s5, s5, 10
	s_add_u32 s4, s4, s5
	s_and_b32 s2, s2, 1
	s_lshl_b32 s2, s2, 7
	s_lshl_b32 s2, s2, s3
	s_add_u32 s4, s4, s2
	s_add_u32 s10, s10, s4
	s_addc_u32 s11, s11, 0
	s_lshl_b32 s2, 32, s3
	s_add_u32 s4, s10, s2
	s_addc_u32 s5, s11, 0
	s_mov_b32 s7, s76
	s_mov_b32 s9, 0x7060302
	v_and_b32_e32 v64, 0x5f, v231
	v_lshlrev_b32_e32 v64, s3, v64
	v_bfe_u32 v65, v231, 5, 1
	v_lshl_or_b32 v64, v65, 3, v64
	v_bfe_u32 v65, v231, 7, 1
	v_lshl_or_b32 v64, v65, 7, v64
	v_bfe_u32 v65, v48, 16, 1
	v_bfe_u32 v66, v49, 16, 1
	v_bfe_u32 v67, v50, 16, 1
	v_bfe_u32 v68, v51, 16, 1
	v_add3_u32 v48, v48, v65, s89
	v_add3_u32 v49, v49, v66, s89
	v_add3_u32 v50, v50, v67, s89
	v_add3_u32 v51, v51, v68, s89
	v_perm_b32 v48, v49, v48, s9
	v_perm_b32 v49, v51, v50, s9
	global_store_dwordx2 v64, v[48:49], s[10:11]
	v_bfe_u32 v65, v52, 16, 1
	v_bfe_u32 v66, v53, 16, 1
	v_bfe_u32 v67, v54, 16, 1
	v_bfe_u32 v68, v55, 16, 1
	v_add3_u32 v52, v52, v65, s89
	v_add3_u32 v53, v53, v66, s89
	v_add3_u32 v54, v54, v67, s89
	v_add3_u32 v55, v55, v68, s89
	v_perm_b32 v52, v53, v52, s9
	v_perm_b32 v53, v55, v54, s9
	global_store_dwordx2 v64, v[52:53], s[10:11] offset:16
	v_bfe_u32 v65, v56, 16, 1
	v_bfe_u32 v66, v57, 16, 1
	v_bfe_u32 v67, v58, 16, 1
	v_bfe_u32 v68, v59, 16, 1
	v_add3_u32 v56, v56, v65, s89
	v_add3_u32 v57, v57, v66, s89
	v_add3_u32 v58, v58, v67, s89
	v_add3_u32 v59, v59, v68, s89
	v_perm_b32 v56, v57, v56, s9
	v_perm_b32 v57, v59, v58, s9
	global_store_dwordx2 v64, v[56:57], s[10:11] offset:32
	v_bfe_u32 v65, v60, 16, 1
	v_bfe_u32 v66, v61, 16, 1
	v_bfe_u32 v67, v62, 16, 1
	v_bfe_u32 v68, v63, 16, 1
	v_add3_u32 v60, v60, v65, s89
	v_add3_u32 v61, v61, v66, s89
	v_add3_u32 v62, v62, v67, s89
	v_add3_u32 v63, v63, v68, s89
	v_perm_b32 v60, v61, v60, s9
	v_perm_b32 v61, v63, v62, s9
	global_store_dwordx2 v64, v[60:61], s[10:11] offset:48
	v_bfe_u32 v65, v16, 16, 1
	v_bfe_u32 v66, v17, 16, 1
	v_bfe_u32 v67, v18, 16, 1
	v_bfe_u32 v68, v19, 16, 1
	v_add3_u32 v16, v16, v65, s89
	v_add3_u32 v17, v17, v66, s89
	v_add3_u32 v18, v18, v67, s89
	v_add3_u32 v19, v19, v68, s89
	v_perm_b32 v16, v17, v16, s9
	v_perm_b32 v17, v19, v18, s9
	global_store_dwordx2 v64, v[16:17], s[10:11] offset:64
	v_bfe_u32 v65, v20, 16, 1
	v_bfe_u32 v66, v21, 16, 1
	v_bfe_u32 v67, v22, 16, 1
	v_bfe_u32 v68, v23, 16, 1
	v_add3_u32 v20, v20, v65, s89
	v_add3_u32 v21, v21, v66, s89
	v_add3_u32 v22, v22, v67, s89
	v_add3_u32 v23, v23, v68, s89
	v_perm_b32 v20, v21, v20, s9
	v_perm_b32 v21, v23, v22, s9
	global_store_dwordx2 v64, v[20:21], s[10:11] offset:80
	v_bfe_u32 v65, v24, 16, 1
	v_bfe_u32 v66, v25, 16, 1
	v_bfe_u32 v67, v26, 16, 1
	v_bfe_u32 v68, v27, 16, 1
	v_add3_u32 v24, v24, v65, s89
	v_add3_u32 v25, v25, v66, s89
	v_add3_u32 v26, v26, v67, s89
	v_add3_u32 v27, v27, v68, s89
	v_perm_b32 v24, v25, v24, s9
	v_perm_b32 v25, v27, v26, s9
	global_store_dwordx2 v64, v[24:25], s[10:11] offset:96
	v_bfe_u32 v65, v28, 16, 1
	v_bfe_u32 v66, v29, 16, 1
	v_bfe_u32 v67, v30, 16, 1
	v_bfe_u32 v68, v31, 16, 1
	v_add3_u32 v28, v28, v65, s89
	v_add3_u32 v29, v29, v66, s89
	v_add3_u32 v30, v30, v67, s89
	v_add3_u32 v31, v31, v68, s89
	v_perm_b32 v28, v29, v28, s9
	v_perm_b32 v29, v31, v30, s9
	global_store_dwordx2 v64, v[28:29], s[10:11] offset:112
	v_bfe_u32 v65, v32, 16, 1
	v_bfe_u32 v66, v33, 16, 1
	v_bfe_u32 v67, v34, 16, 1
	v_bfe_u32 v68, v35, 16, 1
	v_add3_u32 v32, v32, v65, s89
	v_add3_u32 v33, v33, v66, s89
	v_add3_u32 v34, v34, v67, s89
	v_add3_u32 v35, v35, v68, s89
	v_perm_b32 v32, v33, v32, s9
	v_perm_b32 v33, v35, v34, s9
	global_store_dwordx2 v64, v[32:33], s[4:5]
	v_bfe_u32 v65, v36, 16, 1
	v_bfe_u32 v66, v37, 16, 1
	v_bfe_u32 v67, v38, 16, 1
	v_bfe_u32 v68, v39, 16, 1
	v_add3_u32 v36, v36, v65, s89
	v_add3_u32 v37, v37, v66, s89
	v_add3_u32 v38, v38, v67, s89
	v_add3_u32 v39, v39, v68, s89
	v_perm_b32 v36, v37, v36, s9
	v_perm_b32 v37, v39, v38, s9
	global_store_dwordx2 v64, v[36:37], s[4:5] offset:16
	v_bfe_u32 v65, v40, 16, 1
	v_bfe_u32 v66, v41, 16, 1
	v_bfe_u32 v67, v42, 16, 1
	v_bfe_u32 v68, v43, 16, 1
	v_add3_u32 v40, v40, v65, s89
	v_add3_u32 v41, v41, v66, s89
	v_add3_u32 v42, v42, v67, s89
	v_add3_u32 v43, v43, v68, s89
	v_perm_b32 v40, v41, v40, s9
	v_perm_b32 v41, v43, v42, s9
	global_store_dwordx2 v64, v[40:41], s[4:5] offset:32
	v_bfe_u32 v65, v44, 16, 1
	v_bfe_u32 v66, v45, 16, 1
	v_bfe_u32 v67, v46, 16, 1
	v_bfe_u32 v68, v47, 16, 1
	v_add3_u32 v44, v44, v65, s89
	v_add3_u32 v45, v45, v66, s89
	v_add3_u32 v46, v46, v67, s89
	v_add3_u32 v47, v47, v68, s89
	v_perm_b32 v44, v45, v44, s9
	v_perm_b32 v45, v47, v46, s9
	global_store_dwordx2 v64, v[44:45], s[4:5] offset:48
	v_bfe_u32 v65, v0, 16, 1
	v_bfe_u32 v66, v1, 16, 1
	v_bfe_u32 v67, v2, 16, 1
	v_bfe_u32 v68, v3, 16, 1
	v_add3_u32 v0, v0, v65, s89
	v_add3_u32 v1, v1, v66, s89
	v_add3_u32 v2, v2, v67, s89
	v_add3_u32 v3, v3, v68, s89
	v_perm_b32 v0, v1, v0, s9
	v_perm_b32 v1, v3, v2, s9
	global_store_dwordx2 v64, v[0:1], s[4:5] offset:64
	v_bfe_u32 v65, v4, 16, 1
	v_bfe_u32 v66, v5, 16, 1
	v_bfe_u32 v67, v6, 16, 1
	v_bfe_u32 v68, v7, 16, 1
	v_add3_u32 v4, v4, v65, s89
	v_add3_u32 v5, v5, v66, s89
	v_add3_u32 v6, v6, v67, s89
	v_add3_u32 v7, v7, v68, s89
	v_perm_b32 v4, v5, v4, s9
	v_perm_b32 v5, v7, v6, s9
	global_store_dwordx2 v64, v[4:5], s[4:5] offset:80
	v_bfe_u32 v65, v8, 16, 1
	v_bfe_u32 v66, v9, 16, 1
	v_bfe_u32 v67, v10, 16, 1
	v_bfe_u32 v68, v11, 16, 1
	v_add3_u32 v8, v8, v65, s89
	v_add3_u32 v9, v9, v66, s89
	v_add3_u32 v10, v10, v67, s89
	v_add3_u32 v11, v11, v68, s89
	v_perm_b32 v8, v9, v8, s9
	v_perm_b32 v9, v11, v10, s9
	global_store_dwordx2 v64, v[8:9], s[4:5] offset:96
	v_bfe_u32 v65, v12, 16, 1
	v_bfe_u32 v66, v13, 16, 1
	v_bfe_u32 v67, v14, 16, 1
	v_bfe_u32 v68, v15, 16, 1
	v_add3_u32 v12, v12, v65, s89
	v_add3_u32 v13, v13, v66, s89
	v_add3_u32 v14, v14, v67, s89
	v_add3_u32 v15, v15, v68, s89
	v_perm_b32 v12, v13, v12, s9
	v_perm_b32 v13, v15, v14, s9
	global_store_dwordx2 v64, v[12:13], s[4:5] offset:112
	s_mov_b64 s[2:3], exec
	s_branch .LBB0_316

.LBB0_850:
	v_mov_b32_e32 v200, s1
	s_mov_b32 s1, s51
	v_lshl_add_u64 v[94:95], s[0:1], 1, v[70:71]
	v_mov_b32_e32 v226, v74
	v_mov_b32_e32 v227, 0
	v_lshl_add_u64 v[96:97], v[94:95], 0, v[228:229]
	v_lshl_add_u64 v[94:95], v[94:95], 0, v[226:227]
	global_load_dwordx4 v[106:109], v[96:97], off
	global_load_dwordx4 v[110:113], v[94:95], off
	global_load_dwordx4 v[114:117], v[96:97], off offset:32
	global_load_dwordx4 v[118:121], v[94:95], off offset:32
	global_load_dwordx4 v[122:125], v[96:97], off offset:64
	global_load_dwordx4 v[126:129], v[94:95], off offset:64
	global_load_dwordx4 v[130:133], v[96:97], off offset:96
	global_load_dwordx4 v[90:93], v[94:95], off offset:96
	s_mov_b64 s[4:5], 0x2000
	v_add_co_u32_e32 v202, vcc, 0xfffc2000, v76
	s_nop 1
	v_addc_co_u32_e32 v203, vcc, -1, v77, vcc
	global_load_dword v136, v[202:203], off
	v_lshl_add_u64 v[202:203], v[202:203], 0, s[4:5]
	global_load_dword v137, v[202:203], off
	v_lshl_add_u64 v[202:203], v[202:203], 0, s[4:5]
	global_load_dword v138, v[202:203], off
	v_lshl_add_u64 v[202:203], v[202:203], 0, s[4:5]
	global_load_dword v139, v[202:203], off
	v_lshl_add_u64 v[202:203], v[202:203], 0, s[4:5]
	global_load_dword v140, v[202:203], off
	v_lshl_add_u64 v[202:203], v[202:203], 0, s[4:5]
	global_load_dword v141, v[202:203], off
	v_lshl_add_u64 v[202:203], v[202:203], 0, s[4:5]
	global_load_dword v142, v[202:203], off
	v_lshl_add_u64 v[202:203], v[202:203], 0, s[4:5]
	global_load_dword v143, v[202:203], off
	v_lshl_add_u64 v[202:203], v[202:203], 0, s[4:5]
	global_load_dword v144, v[202:203], off
	v_lshl_add_u64 v[202:203], v[202:203], 0, s[4:5]
	global_load_dword v145, v[202:203], off
	v_lshl_add_u64 v[202:203], v[202:203], 0, s[4:5]
	global_load_dword v146, v[202:203], off
	v_lshl_add_u64 v[202:203], v[202:203], 0, s[4:5]
	global_load_dword v147, v[202:203], off
	v_lshl_add_u64 v[202:203], v[202:203], 0, s[4:5]
	global_load_dword v148, v[202:203], off
	v_lshl_add_u64 v[202:203], v[202:203], 0, s[4:5]
	global_load_dword v149, v[202:203], off
	v_lshl_add_u64 v[202:203], v[202:203], 0, s[4:5]
	global_load_dword v150, v[202:203], off
	v_lshl_add_u64 v[202:203], v[202:203], 0, s[4:5]
	global_load_dword v151, v[202:203], off
	v_lshl_add_u64 v[202:203], v[202:203], 0, s[4:5]
	global_load_dword v152, v[202:203], off
	v_lshl_add_u64 v[202:203], v[202:203], 0, s[4:5]
	global_load_dword v153, v[202:203], off
	v_lshl_add_u64 v[202:203], v[202:203], 0, s[4:5]
	global_load_dword v154, v[202:203], off
	v_lshl_add_u64 v[202:203], v[202:203], 0, s[4:5]
	global_load_dword v155, v[202:203], off
	v_lshl_add_u64 v[202:203], v[202:203], 0, s[4:5]
	global_load_dword v156, v[202:203], off
	v_lshl_add_u64 v[202:203], v[202:203], 0, s[4:5]
	global_load_dword v157, v[202:203], off
	v_lshl_add_u64 v[202:203], v[202:203], 0, s[4:5]
	global_load_dword v158, v[202:203], off
	v_lshl_add_u64 v[202:203], v[202:203], 0, s[4:5]
	global_load_dword v159, v[202:203], off
	v_lshl_add_u64 v[202:203], v[202:203], 0, s[4:5]
	global_load_dword v160, v[202:203], off
	v_lshl_add_u64 v[202:203], v[202:203], 0, s[4:5]
	global_load_dword v161, v[202:203], off
	v_lshl_add_u64 v[202:203], v[202:203], 0, s[4:5]
	global_load_dword v162, v[202:203], off
	v_lshl_add_u64 v[202:203], v[202:203], 0, s[4:5]
	global_load_dword v163, v[202:203], off
	v_lshl_add_u64 v[202:203], v[202:203], 0, s[4:5]
	global_load_dword v164, v[202:203], off
	v_lshl_add_u64 v[202:203], v[202:203], 0, s[4:5]
	global_load_dword v165, v[202:203], off
	v_lshl_add_u64 v[202:203], v[202:203], 0, s[4:5]
	global_load_dword v166, v[202:203], off
	v_lshl_add_u64 v[202:203], v[202:203], 0, s[4:5]
	global_load_dword v167, v[202:203], off
	v_lshl_add_u64 v[202:203], v[202:203], 0, s[4:5]
	global_load_dword v168, v[202:203], off
	v_lshl_add_u64 v[202:203], v[202:203], 0, s[4:5]
	global_load_dword v169, v[202:203], off
	v_lshl_add_u64 v[202:203], v[202:203], 0, s[4:5]
	global_load_dword v170, v[202:203], off
	v_lshl_add_u64 v[202:203], v[202:203], 0, s[4:5]
	global_load_dword v171, v[202:203], off
	v_lshl_add_u64 v[202:203], v[202:203], 0, s[4:5]
	global_load_dword v172, v[202:203], off
	v_lshl_add_u64 v[202:203], v[202:203], 0, s[4:5]
	global_load_dword v173, v[202:203], off
	v_lshl_add_u64 v[202:203], v[202:203], 0, s[4:5]
	global_load_dword v174, v[202:203], off
	v_lshl_add_u64 v[202:203], v[202:203], 0, s[4:5]
	global_load_dword v175, v[202:203], off
	v_lshl_add_u64 v[202:203], v[202:203], 0, s[4:5]
	global_load_dword v176, v[202:203], off
	v_lshl_add_u64 v[202:203], v[202:203], 0, s[4:5]
	global_load_dword v177, v[202:203], off
	v_lshl_add_u64 v[202:203], v[202:203], 0, s[4:5]
	global_load_dword v178, v[202:203], off
	v_lshl_add_u64 v[202:203], v[202:203], 0, s[4:5]
	global_load_dword v179, v[202:203], off
	v_lshl_add_u64 v[202:203], v[202:203], 0, s[4:5]
	global_load_dword v180, v[202:203], off
	v_lshl_add_u64 v[202:203], v[202:203], 0, s[4:5]
	global_load_dword v181, v[202:203], off
	v_lshl_add_u64 v[202:203], v[202:203], 0, s[4:5]
	global_load_dword v182, v[202:203], off
	v_lshl_add_u64 v[202:203], v[202:203], 0, s[4:5]
	global_load_dword v183, v[202:203], off
	v_lshl_add_u64 v[202:203], v[202:203], 0, s[4:5]
	global_load_dword v184, v[202:203], off
	v_lshl_add_u64 v[202:203], v[202:203], 0, s[4:5]
	global_load_dword v185, v[202:203], off
	v_lshl_add_u64 v[202:203], v[202:203], 0, s[4:5]
	global_load_dword v186, v[202:203], off
	v_lshl_add_u64 v[202:203], v[202:203], 0, s[4:5]
	global_load_dword v187, v[202:203], off
	v_lshl_add_u64 v[202:203], v[202:203], 0, s[4:5]
	global_load_dword v188, v[202:203], off
	v_lshl_add_u64 v[202:203], v[202:203], 0, s[4:5]
	global_load_dword v189, v[202:203], off
	v_lshl_add_u64 v[202:203], v[202:203], 0, s[4:5]
	global_load_dword v190, v[202:203], off
	v_lshl_add_u64 v[202:203], v[202:203], 0, s[4:5]
	global_load_dword v191, v[202:203], off
	v_lshl_add_u64 v[202:203], v[202:203], 0, s[4:5]
	global_load_dword v192, v[202:203], off
	v_lshl_add_u64 v[202:203], v[202:203], 0, s[4:5]
	global_load_dword v193, v[202:203], off
	v_lshl_add_u64 v[202:203], v[202:203], 0, s[4:5]
	global_load_dword v194, v[202:203], off
	v_lshl_add_u64 v[202:203], v[202:203], 0, s[4:5]
	global_load_dword v195, v[202:203], off
	v_lshl_add_u64 v[202:203], v[202:203], 0, s[4:5]
	global_load_dword v196, v[202:203], off
	v_lshl_add_u64 v[202:203], v[202:203], 0, s[4:5]
	global_load_dword v197, v[202:203], off
	v_lshl_add_u64 v[202:203], v[202:203], 0, s[4:5]
	global_load_dword v198, v[202:203], off
	v_lshl_add_u64 v[202:203], v[202:203], 0, s[4:5]
	global_load_dword v199, v[202:203], off
	ds_read_b128 v[204:207], v200
	ds_read_b128 v[208:211], v200 offset:16
	ds_read_b128 v[212:215], v200 offset:32
	ds_read_b128 v[216:219], v200 offset:48
	s_waitcnt vmcnt(56)
	v_mul_f32_e32 v220, 0x3d372713, v136
	v_mul_f32_e32 v221, 0x3d372713, v137
	v_mul_f32_e32 v222, 0x3d372713, v138
	v_mul_f32_e32 v223, 0x3d372713, v139
	v_mul_f32_e32 v224, 0x3d372713, v140
	v_mul_f32_e32 v225, 0x3d372713, v141
	v_mul_f32_e32 v226, 0x3d372713, v142
	v_mul_f32_e32 v227, 0x3d372713, v143
	v_mul_f32_e32 v220, v136, v220
	v_mul_f32_e32 v221, v137, v221
	v_mul_f32_e32 v222, v138, v222
	v_mul_f32_e32 v223, v139, v223
	v_mul_f32_e32 v224, v140, v224
	v_mul_f32_e32 v225, v141, v225
	v_mul_f32_e32 v226, v142, v226
	v_mul_f32_e32 v227, v143, v227
	v_fma_f32 v220, v136, v220, v136
	v_fma_f32 v221, v137, v221, v137
	v_fma_f32 v222, v138, v222, v138
	v_fma_f32 v223, v139, v223, v139
	v_fma_f32 v224, v140, v224, v140
	v_fma_f32 v225, v141, v225, v141
	v_fma_f32 v226, v142, v226, v142
	v_fma_f32 v227, v143, v227, v143
	v_mul_f32_e32 v220, 0xbfcc422a, v220
	v_mul_f32_e32 v221, 0xbfcc422a, v221
	v_mul_f32_e32 v222, 0xbfcc422a, v222
	v_mul_f32_e32 v223, 0xbfcc422a, v223
	v_mul_f32_e32 v224, 0xbfcc422a, v224
	v_mul_f32_e32 v225, 0xbfcc422a, v225
	v_mul_f32_e32 v226, 0xbfcc422a, v226
	v_mul_f32_e32 v227, 0xbfcc422a, v227
	v_mul_f32_e32 v220, 0x3fb8aa3b, v220
	v_mul_f32_e32 v221, 0x3fb8aa3b, v221
	v_mul_f32_e32 v222, 0x3fb8aa3b, v222
	v_mul_f32_e32 v223, 0x3fb8aa3b, v223
	v_mul_f32_e32 v224, 0x3fb8aa3b, v224
	v_mul_f32_e32 v225, 0x3fb8aa3b, v225
	v_mul_f32_e32 v226, 0x3fb8aa3b, v226
	v_mul_f32_e32 v227, 0x3fb8aa3b, v227
	v_exp_f32_e32 v220, v220
	v_exp_f32_e32 v221, v221
	v_exp_f32_e32 v222, v222
	v_exp_f32_e32 v223, v223
	v_exp_f32_e32 v224, v224
	v_exp_f32_e32 v225, v225
	v_exp_f32_e32 v226, v226
	v_exp_f32_e32 v227, v227
	v_add_f32_e32 v220, 1.0, v220
	v_add_f32_e32 v221, 1.0, v221
	v_add_f32_e32 v222, 1.0, v222
	v_add_f32_e32 v223, 1.0, v223
	v_add_f32_e32 v224, 1.0, v224
	v_add_f32_e32 v225, 1.0, v225
	v_add_f32_e32 v226, 1.0, v226
	v_add_f32_e32 v227, 1.0, v227
	v_rcp_f32_e32 v220, v220
	v_rcp_f32_e32 v221, v221
	v_rcp_f32_e32 v222, v222
	v_rcp_f32_e32 v223, v223
	v_rcp_f32_e32 v224, v224
	v_rcp_f32_e32 v225, v225
	v_rcp_f32_e32 v226, v226
	v_rcp_f32_e32 v227, v227
	v_mul_f32_e32 v136, v136, v220
	v_mul_f32_e32 v137, v137, v221
	v_mul_f32_e32 v138, v138, v222
	v_mul_f32_e32 v139, v139, v223
	v_mul_f32_e32 v140, v140, v224
	v_mul_f32_e32 v141, v141, v225
	v_mul_f32_e32 v142, v142, v226
	v_mul_f32_e32 v143, v143, v227
	s_waitcnt lgkmcnt(2)
	v_mul_f32_e32 v136, v204, v136
	v_mul_f32_e32 v137, v205, v137
	v_mul_f32_e32 v138, v206, v138
	v_mul_f32_e32 v139, v207, v139
	v_mul_f32_e32 v140, v208, v140
	v_mul_f32_e32 v141, v209, v141
	v_mul_f32_e32 v142, v210, v142
	v_mul_f32_e32 v143, v211, v143
	v_mul_f32_e32 v136, v66, v136
	v_mul_f32_e32 v137, v66, v137
	v_mul_f32_e32 v138, v66, v138
	v_mul_f32_e32 v139, v66, v139
	v_mul_f32_e32 v140, v66, v140
	v_mul_f32_e32 v141, v66, v141
	v_mul_f32_e32 v142, v66, v142
	v_mul_f32_e32 v143, v66, v143
	v_bfe_u32 v220, v136, 16, 1
	v_bfe_u32 v221, v137, 16, 1
	v_bfe_u32 v222, v138, 16, 1
	v_bfe_u32 v223, v139, 16, 1
	v_bfe_u32 v224, v140, 16, 1
	v_bfe_u32 v225, v141, 16, 1
	v_bfe_u32 v226, v142, 16, 1
	v_bfe_u32 v227, v143, 16, 1
	v_add3_u32 v136, v136, v220, s89
	v_add3_u32 v137, v137, v221, s89
	v_add3_u32 v138, v138, v222, s89
	v_add3_u32 v139, v139, v223, s89
	v_add3_u32 v140, v140, v224, s89
	v_add3_u32 v141, v141, v225, s89
	v_add3_u32 v142, v142, v226, s89
	v_add3_u32 v143, v143, v227, s89
	v_lshrrev_b32_e32 v224, 16, v136
	v_lshrrev_b32_e32 v225, 16, v138
	v_lshrrev_b32_e32 v226, 16, v140
	v_lshrrev_b32_e32 v227, 16, v142
	v_and_or_b32 v220, v137, s75, v224
	v_and_or_b32 v221, v139, s75, v225
	v_and_or_b32 v222, v141, s75, v226
	v_and_or_b32 v223, v143, s75, v227
	ds_write_b128 v75, v[220:223]
	ds_read_b128 v[204:207], v200 offset:64
	ds_read_b128 v[208:211], v200 offset:80
	s_waitcnt vmcnt(48)
	v_mul_f32_e32 v220, 0x3d372713, v144
	v_mul_f32_e32 v221, 0x3d372713, v145
	v_mul_f32_e32 v222, 0x3d372713, v146
	v_mul_f32_e32 v223, 0x3d372713, v147
	v_mul_f32_e32 v224, 0x3d372713, v148
	v_mul_f32_e32 v225, 0x3d372713, v149
	v_mul_f32_e32 v226, 0x3d372713, v150
	v_mul_f32_e32 v227, 0x3d372713, v151
	v_mul_f32_e32 v220, v144, v220
	v_mul_f32_e32 v221, v145, v221
	v_mul_f32_e32 v222, v146, v222
	v_mul_f32_e32 v223, v147, v223
	v_mul_f32_e32 v224, v148, v224
	v_mul_f32_e32 v225, v149, v225
	v_mul_f32_e32 v226, v150, v226
	v_mul_f32_e32 v227, v151, v227
	v_fma_f32 v220, v144, v220, v144
	v_fma_f32 v221, v145, v221, v145
	v_fma_f32 v222, v146, v222, v146
	v_fma_f32 v223, v147, v223, v147
	v_fma_f32 v224, v148, v224, v148
	v_fma_f32 v225, v149, v225, v149
	v_fma_f32 v226, v150, v226, v150
	v_fma_f32 v227, v151, v227, v151
	v_mul_f32_e32 v220, 0xbfcc422a, v220
	v_mul_f32_e32 v221, 0xbfcc422a, v221
	v_mul_f32_e32 v222, 0xbfcc422a, v222
	v_mul_f32_e32 v223, 0xbfcc422a, v223
	v_mul_f32_e32 v224, 0xbfcc422a, v224
	v_mul_f32_e32 v225, 0xbfcc422a, v225
	v_mul_f32_e32 v226, 0xbfcc422a, v226
	v_mul_f32_e32 v227, 0xbfcc422a, v227
	v_mul_f32_e32 v220, 0x3fb8aa3b, v220
	v_mul_f32_e32 v221, 0x3fb8aa3b, v221
	v_mul_f32_e32 v222, 0x3fb8aa3b, v222
	v_mul_f32_e32 v223, 0x3fb8aa3b, v223
	v_mul_f32_e32 v224, 0x3fb8aa3b, v224
	v_mul_f32_e32 v225, 0x3fb8aa3b, v225
	v_mul_f32_e32 v226, 0x3fb8aa3b, v226
	v_mul_f32_e32 v227, 0x3fb8aa3b, v227
	v_exp_f32_e32 v220, v220
	v_exp_f32_e32 v221, v221
	v_exp_f32_e32 v222, v222
	v_exp_f32_e32 v223, v223
	v_exp_f32_e32 v224, v224
	v_exp_f32_e32 v225, v225
	v_exp_f32_e32 v226, v226
	v_exp_f32_e32 v227, v227
	v_add_f32_e32 v220, 1.0, v220
	v_add_f32_e32 v221, 1.0, v221
	v_add_f32_e32 v222, 1.0, v222
	v_add_f32_e32 v223, 1.0, v223
	v_add_f32_e32 v224, 1.0, v224
	v_add_f32_e32 v225, 1.0, v225
	v_add_f32_e32 v226, 1.0, v226
	v_add_f32_e32 v227, 1.0, v227
	v_rcp_f32_e32 v220, v220
	v_rcp_f32_e32 v221, v221
	v_rcp_f32_e32 v222, v222
	v_rcp_f32_e32 v223, v223
	v_rcp_f32_e32 v224, v224
	v_rcp_f32_e32 v225, v225
	v_rcp_f32_e32 v226, v226
	v_rcp_f32_e32 v227, v227
	v_mul_f32_e32 v144, v144, v220
	v_mul_f32_e32 v145, v145, v221
	v_mul_f32_e32 v146, v146, v222
	v_mul_f32_e32 v147, v147, v223
	v_mul_f32_e32 v148, v148, v224
	v_mul_f32_e32 v149, v149, v225
	v_mul_f32_e32 v150, v150, v226
	v_mul_f32_e32 v151, v151, v227
	s_waitcnt lgkmcnt(2)
	v_mul_f32_e32 v144, v212, v144
	v_mul_f32_e32 v145, v213, v145
	v_mul_f32_e32 v146, v214, v146
	v_mul_f32_e32 v147, v215, v147
	v_mul_f32_e32 v148, v216, v148
	v_mul_f32_e32 v149, v217, v149
	v_mul_f32_e32 v150, v218, v150
	v_mul_f32_e32 v151, v219, v151
	v_mul_f32_e32 v144, v66, v144
	v_mul_f32_e32 v145, v66, v145
	v_mul_f32_e32 v146, v66, v146
	v_mul_f32_e32 v147, v66, v147
	v_mul_f32_e32 v148, v66, v148
	v_mul_f32_e32 v149, v66, v149
	v_mul_f32_e32 v150, v66, v150
	v_mul_f32_e32 v151, v66, v151
	v_bfe_u32 v220, v144, 16, 1
	v_bfe_u32 v221, v145, 16, 1
	v_bfe_u32 v222, v146, 16, 1
	v_bfe_u32 v223, v147, 16, 1
	v_bfe_u32 v224, v148, 16, 1
	v_bfe_u32 v225, v149, 16, 1
	v_bfe_u32 v226, v150, 16, 1
	v_bfe_u32 v227, v151, 16, 1
	v_add3_u32 v144, v144, v220, s89
	v_add3_u32 v145, v145, v221, s89
	v_add3_u32 v146, v146, v222, s89
	v_add3_u32 v147, v147, v223, s89
	v_add3_u32 v148, v148, v224, s89
	v_add3_u32 v149, v149, v225, s89
	v_add3_u32 v150, v150, v226, s89
	v_add3_u32 v151, v151, v227, s89
	v_lshrrev_b32_e32 v224, 16, v144
	v_lshrrev_b32_e32 v225, 16, v146
	v_lshrrev_b32_e32 v226, 16, v148
	v_lshrrev_b32_e32 v227, 16, v150
	v_and_or_b32 v220, v145, s75, v224
	v_and_or_b32 v221, v147, s75, v225
	v_and_or_b32 v222, v149, s75, v226
	v_and_or_b32 v223, v151, s75, v227
	ds_write_b128 v75, v[220:223] offset:16
	ds_read_b128 v[212:215], v200 offset:96
	ds_read_b128 v[216:219], v200 offset:112
	s_waitcnt vmcnt(40)
	v_mul_f32_e32 v220, 0x3d372713, v152
	v_mul_f32_e32 v221, 0x3d372713, v153
	v_mul_f32_e32 v222, 0x3d372713, v154
	v_mul_f32_e32 v223, 0x3d372713, v155
	v_mul_f32_e32 v224, 0x3d372713, v156
	v_mul_f32_e32 v225, 0x3d372713, v157
	v_mul_f32_e32 v226, 0x3d372713, v158
	v_mul_f32_e32 v227, 0x3d372713, v159
	v_mul_f32_e32 v220, v152, v220
	v_mul_f32_e32 v221, v153, v221
	v_mul_f32_e32 v222, v154, v222
	v_mul_f32_e32 v223, v155, v223
	v_mul_f32_e32 v224, v156, v224
	v_mul_f32_e32 v225, v157, v225
	v_mul_f32_e32 v226, v158, v226
	v_mul_f32_e32 v227, v159, v227
	v_fma_f32 v220, v152, v220, v152
	v_fma_f32 v221, v153, v221, v153
	v_fma_f32 v222, v154, v222, v154
	v_fma_f32 v223, v155, v223, v155
	v_fma_f32 v224, v156, v224, v156
	v_fma_f32 v225, v157, v225, v157
	v_fma_f32 v226, v158, v226, v158
	v_fma_f32 v227, v159, v227, v159
	v_mul_f32_e32 v220, 0xbfcc422a, v220
	v_mul_f32_e32 v221, 0xbfcc422a, v221
	v_mul_f32_e32 v222, 0xbfcc422a, v222
	v_mul_f32_e32 v223, 0xbfcc422a, v223
	v_mul_f32_e32 v224, 0xbfcc422a, v224
	v_mul_f32_e32 v225, 0xbfcc422a, v225
	v_mul_f32_e32 v226, 0xbfcc422a, v226
	v_mul_f32_e32 v227, 0xbfcc422a, v227
	v_mul_f32_e32 v220, 0x3fb8aa3b, v220
	v_mul_f32_e32 v221, 0x3fb8aa3b, v221
	v_mul_f32_e32 v222, 0x3fb8aa3b, v222
	v_mul_f32_e32 v223, 0x3fb8aa3b, v223
	v_mul_f32_e32 v224, 0x3fb8aa3b, v224
	v_mul_f32_e32 v225, 0x3fb8aa3b, v225
	v_mul_f32_e32 v226, 0x3fb8aa3b, v226
	v_mul_f32_e32 v227, 0x3fb8aa3b, v227
	v_exp_f32_e32 v220, v220
	v_exp_f32_e32 v221, v221
	v_exp_f32_e32 v222, v222
	v_exp_f32_e32 v223, v223
	v_exp_f32_e32 v224, v224
	v_exp_f32_e32 v225, v225
	v_exp_f32_e32 v226, v226
	v_exp_f32_e32 v227, v227
	v_add_f32_e32 v220, 1.0, v220
	v_add_f32_e32 v221, 1.0, v221
	v_add_f32_e32 v222, 1.0, v222
	v_add_f32_e32 v223, 1.0, v223
	v_add_f32_e32 v224, 1.0, v224
	v_add_f32_e32 v225, 1.0, v225
	v_add_f32_e32 v226, 1.0, v226
	v_add_f32_e32 v227, 1.0, v227
	v_rcp_f32_e32 v220, v220
	v_rcp_f32_e32 v221, v221
	v_rcp_f32_e32 v222, v222
	v_rcp_f32_e32 v223, v223
	v_rcp_f32_e32 v224, v224
	v_rcp_f32_e32 v225, v225
	v_rcp_f32_e32 v226, v226
	v_rcp_f32_e32 v227, v227
	v_mul_f32_e32 v152, v152, v220
	v_mul_f32_e32 v153, v153, v221
	v_mul_f32_e32 v154, v154, v222
	v_mul_f32_e32 v155, v155, v223
	v_mul_f32_e32 v156, v156, v224
	v_mul_f32_e32 v157, v157, v225
	v_mul_f32_e32 v158, v158, v226
	v_mul_f32_e32 v159, v159, v227
	s_waitcnt lgkmcnt(2)
	v_mul_f32_e32 v152, v204, v152
	v_mul_f32_e32 v153, v205, v153
	v_mul_f32_e32 v154, v206, v154
	v_mul_f32_e32 v155, v207, v155
	v_mul_f32_e32 v156, v208, v156
	v_mul_f32_e32 v157, v209, v157
	v_mul_f32_e32 v158, v210, v158
	v_mul_f32_e32 v159, v211, v159
	v_mul_f32_e32 v152, v66, v152
	v_mul_f32_e32 v153, v66, v153
	v_mul_f32_e32 v154, v66, v154
	v_mul_f32_e32 v155, v66, v155
	v_mul_f32_e32 v156, v66, v156
	v_mul_f32_e32 v157, v66, v157
	v_mul_f32_e32 v158, v66, v158
	v_mul_f32_e32 v159, v66, v159
	v_bfe_u32 v220, v152, 16, 1
	v_bfe_u32 v221, v153, 16, 1
	v_bfe_u32 v222, v154, 16, 1
	v_bfe_u32 v223, v155, 16, 1
	v_bfe_u32 v224, v156, 16, 1
	v_bfe_u32 v225, v157, 16, 1
	v_bfe_u32 v226, v158, 16, 1
	v_bfe_u32 v227, v159, 16, 1
	v_add3_u32 v152, v152, v220, s89
	v_add3_u32 v153, v153, v221, s89
	v_add3_u32 v154, v154, v222, s89
	v_add3_u32 v155, v155, v223, s89
	v_add3_u32 v156, v156, v224, s89
	v_add3_u32 v157, v157, v225, s89
	v_add3_u32 v158, v158, v226, s89
	v_add3_u32 v159, v159, v227, s89
	v_lshrrev_b32_e32 v224, 16, v152
	v_lshrrev_b32_e32 v225, 16, v154
	v_lshrrev_b32_e32 v226, 16, v156
	v_lshrrev_b32_e32 v227, 16, v158
	v_and_or_b32 v220, v153, s75, v224
	v_and_or_b32 v221, v155, s75, v225
	v_and_or_b32 v222, v157, s75, v226
	v_and_or_b32 v223, v159, s75, v227
	ds_write_b128 v75, v[220:223] offset:32
	ds_read_b128 v[204:207], v200 offset:128
	ds_read_b128 v[208:211], v200 offset:144
	s_waitcnt vmcnt(32)
	v_mul_f32_e32 v220, 0x3d372713, v160
	v_mul_f32_e32 v221, 0x3d372713, v161
	v_mul_f32_e32 v222, 0x3d372713, v162
	v_mul_f32_e32 v223, 0x3d372713, v163
	v_mul_f32_e32 v224, 0x3d372713, v164
	v_mul_f32_e32 v225, 0x3d372713, v165
	v_mul_f32_e32 v226, 0x3d372713, v166
	v_mul_f32_e32 v227, 0x3d372713, v167
	v_mul_f32_e32 v220, v160, v220
	v_mul_f32_e32 v221, v161, v221
	v_mul_f32_e32 v222, v162, v222
	v_mul_f32_e32 v223, v163, v223
	v_mul_f32_e32 v224, v164, v224
	v_mul_f32_e32 v225, v165, v225
	v_mul_f32_e32 v226, v166, v226
	v_mul_f32_e32 v227, v167, v227
	v_fma_f32 v220, v160, v220, v160
	v_fma_f32 v221, v161, v221, v161
	v_fma_f32 v222, v162, v222, v162
	v_fma_f32 v223, v163, v223, v163
	v_fma_f32 v224, v164, v224, v164
	v_fma_f32 v225, v165, v225, v165
	v_fma_f32 v226, v166, v226, v166
	v_fma_f32 v227, v167, v227, v167
	v_mul_f32_e32 v220, 0xbfcc422a, v220
	v_mul_f32_e32 v221, 0xbfcc422a, v221
	v_mul_f32_e32 v222, 0xbfcc422a, v222
	v_mul_f32_e32 v223, 0xbfcc422a, v223
	v_mul_f32_e32 v224, 0xbfcc422a, v224
	v_mul_f32_e32 v225, 0xbfcc422a, v225
	v_mul_f32_e32 v226, 0xbfcc422a, v226
	v_mul_f32_e32 v227, 0xbfcc422a, v227
	v_mul_f32_e32 v220, 0x3fb8aa3b, v220
	v_mul_f32_e32 v221, 0x3fb8aa3b, v221
	v_mul_f32_e32 v222, 0x3fb8aa3b, v222
	v_mul_f32_e32 v223, 0x3fb8aa3b, v223
	v_mul_f32_e32 v224, 0x3fb8aa3b, v224
	v_mul_f32_e32 v225, 0x3fb8aa3b, v225
	v_mul_f32_e32 v226, 0x3fb8aa3b, v226
	v_mul_f32_e32 v227, 0x3fb8aa3b, v227
	v_exp_f32_e32 v220, v220
	v_exp_f32_e32 v221, v221
	v_exp_f32_e32 v222, v222
	v_exp_f32_e32 v223, v223
	v_exp_f32_e32 v224, v224
	v_exp_f32_e32 v225, v225
	v_exp_f32_e32 v226, v226
	v_exp_f32_e32 v227, v227
	v_add_f32_e32 v220, 1.0, v220
	v_add_f32_e32 v221, 1.0, v221
	v_add_f32_e32 v222, 1.0, v222
	v_add_f32_e32 v223, 1.0, v223
	v_add_f32_e32 v224, 1.0, v224
	v_add_f32_e32 v225, 1.0, v225
	v_add_f32_e32 v226, 1.0, v226
	v_add_f32_e32 v227, 1.0, v227
	v_rcp_f32_e32 v220, v220
	v_rcp_f32_e32 v221, v221
	v_rcp_f32_e32 v222, v222
	v_rcp_f32_e32 v223, v223
	v_rcp_f32_e32 v224, v224
	v_rcp_f32_e32 v225, v225
	v_rcp_f32_e32 v226, v226
	v_rcp_f32_e32 v227, v227
	v_mul_f32_e32 v160, v160, v220
	v_mul_f32_e32 v161, v161, v221
	v_mul_f32_e32 v162, v162, v222
	v_mul_f32_e32 v163, v163, v223
	v_mul_f32_e32 v164, v164, v224
	v_mul_f32_e32 v165, v165, v225
	v_mul_f32_e32 v166, v166, v226
	v_mul_f32_e32 v167, v167, v227
	s_waitcnt lgkmcnt(2)
	v_mul_f32_e32 v160, v212, v160
	v_mul_f32_e32 v161, v213, v161
	v_mul_f32_e32 v162, v214, v162
	v_mul_f32_e32 v163, v215, v163
	v_mul_f32_e32 v164, v216, v164
	v_mul_f32_e32 v165, v217, v165
	v_mul_f32_e32 v166, v218, v166
	v_mul_f32_e32 v167, v219, v167
	v_mul_f32_e32 v160, v66, v160
	v_mul_f32_e32 v161, v66, v161
	v_mul_f32_e32 v162, v66, v162
	v_mul_f32_e32 v163, v66, v163
	v_mul_f32_e32 v164, v66, v164
	v_mul_f32_e32 v165, v66, v165
	v_mul_f32_e32 v166, v66, v166
	v_mul_f32_e32 v167, v66, v167
	v_bfe_u32 v220, v160, 16, 1
	v_bfe_u32 v221, v161, 16, 1
	v_bfe_u32 v222, v162, 16, 1
	v_bfe_u32 v223, v163, 16, 1
	v_bfe_u32 v224, v164, 16, 1
	v_bfe_u32 v225, v165, 16, 1
	v_bfe_u32 v226, v166, 16, 1
	v_bfe_u32 v227, v167, 16, 1
	v_add3_u32 v160, v160, v220, s89
	v_add3_u32 v161, v161, v221, s89
	v_add3_u32 v162, v162, v222, s89
	v_add3_u32 v163, v163, v223, s89
	v_add3_u32 v164, v164, v224, s89
	v_add3_u32 v165, v165, v225, s89
	v_add3_u32 v166, v166, v226, s89
	v_add3_u32 v167, v167, v227, s89
	v_lshrrev_b32_e32 v224, 16, v160
	v_lshrrev_b32_e32 v225, 16, v162
	v_lshrrev_b32_e32 v226, 16, v164
	v_lshrrev_b32_e32 v227, 16, v166
	v_and_or_b32 v220, v161, s75, v224
	v_and_or_b32 v221, v163, s75, v225
	v_and_or_b32 v222, v165, s75, v226
	v_and_or_b32 v223, v167, s75, v227
	ds_write_b128 v75, v[220:223] offset:48
	ds_read_b128 v[212:215], v200 offset:160
	ds_read_b128 v[216:219], v200 offset:176
	s_waitcnt vmcnt(24)
	v_mul_f32_e32 v220, 0x3d372713, v168
	v_mul_f32_e32 v221, 0x3d372713, v169
	v_mul_f32_e32 v222, 0x3d372713, v170
	v_mul_f32_e32 v223, 0x3d372713, v171
	v_mul_f32_e32 v224, 0x3d372713, v172
	v_mul_f32_e32 v225, 0x3d372713, v173
	v_mul_f32_e32 v226, 0x3d372713, v174
	v_mul_f32_e32 v227, 0x3d372713, v175
	v_mul_f32_e32 v220, v168, v220
	v_mul_f32_e32 v221, v169, v221
	v_mul_f32_e32 v222, v170, v222
	v_mul_f32_e32 v223, v171, v223
	v_mul_f32_e32 v224, v172, v224
	v_mul_f32_e32 v225, v173, v225
	v_mul_f32_e32 v226, v174, v226
	v_mul_f32_e32 v227, v175, v227
	v_fma_f32 v220, v168, v220, v168
	v_fma_f32 v221, v169, v221, v169
	v_fma_f32 v222, v170, v222, v170
	v_fma_f32 v223, v171, v223, v171
	v_fma_f32 v224, v172, v224, v172
	v_fma_f32 v225, v173, v225, v173
	v_fma_f32 v226, v174, v226, v174
	v_fma_f32 v227, v175, v227, v175
	v_mul_f32_e32 v220, 0xbfcc422a, v220
	v_mul_f32_e32 v221, 0xbfcc422a, v221
	v_mul_f32_e32 v222, 0xbfcc422a, v222
	v_mul_f32_e32 v223, 0xbfcc422a, v223
	v_mul_f32_e32 v224, 0xbfcc422a, v224
	v_mul_f32_e32 v225, 0xbfcc422a, v225
	v_mul_f32_e32 v226, 0xbfcc422a, v226
	v_mul_f32_e32 v227, 0xbfcc422a, v227
	v_mul_f32_e32 v220, 0x3fb8aa3b, v220
	v_mul_f32_e32 v221, 0x3fb8aa3b, v221
	v_mul_f32_e32 v222, 0x3fb8aa3b, v222
	v_mul_f32_e32 v223, 0x3fb8aa3b, v223
	v_mul_f32_e32 v224, 0x3fb8aa3b, v224
	v_mul_f32_e32 v225, 0x3fb8aa3b, v225
	v_mul_f32_e32 v226, 0x3fb8aa3b, v226
	v_mul_f32_e32 v227, 0x3fb8aa3b, v227
	v_exp_f32_e32 v220, v220
	v_exp_f32_e32 v221, v221
	v_exp_f32_e32 v222, v222
	v_exp_f32_e32 v223, v223
	v_exp_f32_e32 v224, v224
	v_exp_f32_e32 v225, v225
	v_exp_f32_e32 v226, v226
	v_exp_f32_e32 v227, v227
	v_add_f32_e32 v220, 1.0, v220
	v_add_f32_e32 v221, 1.0, v221
	v_add_f32_e32 v222, 1.0, v222
	v_add_f32_e32 v223, 1.0, v223
	v_add_f32_e32 v224, 1.0, v224
	v_add_f32_e32 v225, 1.0, v225
	v_add_f32_e32 v226, 1.0, v226
	v_add_f32_e32 v227, 1.0, v227
	v_rcp_f32_e32 v220, v220
	v_rcp_f32_e32 v221, v221
	v_rcp_f32_e32 v222, v222
	v_rcp_f32_e32 v223, v223
	v_rcp_f32_e32 v224, v224
	v_rcp_f32_e32 v225, v225
	v_rcp_f32_e32 v226, v226
	v_rcp_f32_e32 v227, v227
	v_mul_f32_e32 v168, v168, v220
	v_mul_f32_e32 v169, v169, v221
	v_mul_f32_e32 v170, v170, v222
	v_mul_f32_e32 v171, v171, v223
	v_mul_f32_e32 v172, v172, v224
	v_mul_f32_e32 v173, v173, v225
	v_mul_f32_e32 v174, v174, v226
	v_mul_f32_e32 v175, v175, v227
	s_waitcnt lgkmcnt(2)
	v_mul_f32_e32 v168, v204, v168
	v_mul_f32_e32 v169, v205, v169
	v_mul_f32_e32 v170, v206, v170
	v_mul_f32_e32 v171, v207, v171
	v_mul_f32_e32 v172, v208, v172
	v_mul_f32_e32 v173, v209, v173
	v_mul_f32_e32 v174, v210, v174
	v_mul_f32_e32 v175, v211, v175
	v_mul_f32_e32 v168, v66, v168
	v_mul_f32_e32 v169, v66, v169
	v_mul_f32_e32 v170, v66, v170
	v_mul_f32_e32 v171, v66, v171
	v_mul_f32_e32 v172, v66, v172
	v_mul_f32_e32 v173, v66, v173
	v_mul_f32_e32 v174, v66, v174
	v_mul_f32_e32 v175, v66, v175
	v_bfe_u32 v220, v168, 16, 1
	v_bfe_u32 v221, v169, 16, 1
	v_bfe_u32 v222, v170, 16, 1
	v_bfe_u32 v223, v171, 16, 1
	v_bfe_u32 v224, v172, 16, 1
	v_bfe_u32 v225, v173, 16, 1
	v_bfe_u32 v226, v174, 16, 1
	v_bfe_u32 v227, v175, 16, 1
	v_add3_u32 v168, v168, v220, s89
	v_add3_u32 v169, v169, v221, s89
	v_add3_u32 v170, v170, v222, s89
	v_add3_u32 v171, v171, v223, s89
	v_add3_u32 v172, v172, v224, s89
	v_add3_u32 v173, v173, v225, s89
	v_add3_u32 v174, v174, v226, s89
	v_add3_u32 v175, v175, v227, s89
	v_lshrrev_b32_e32 v224, 16, v168
	v_lshrrev_b32_e32 v225, 16, v170
	v_lshrrev_b32_e32 v226, 16, v172
	v_lshrrev_b32_e32 v227, 16, v174
	v_and_or_b32 v220, v169, s75, v224
	v_and_or_b32 v221, v171, s75, v225
	v_and_or_b32 v222, v173, s75, v226
	v_and_or_b32 v223, v175, s75, v227
	ds_write_b128 v75, v[220:223] offset:64
	ds_read_b128 v[204:207], v200 offset:192
	ds_read_b128 v[208:211], v200 offset:208
	s_waitcnt vmcnt(16)
	v_mul_f32_e32 v220, 0x3d372713, v176
	v_mul_f32_e32 v221, 0x3d372713, v177
	v_mul_f32_e32 v222, 0x3d372713, v178
	v_mul_f32_e32 v223, 0x3d372713, v179
	v_mul_f32_e32 v224, 0x3d372713, v180
	v_mul_f32_e32 v225, 0x3d372713, v181
	v_mul_f32_e32 v226, 0x3d372713, v182
	v_mul_f32_e32 v227, 0x3d372713, v183
	v_mul_f32_e32 v220, v176, v220
	v_mul_f32_e32 v221, v177, v221
	v_mul_f32_e32 v222, v178, v222
	v_mul_f32_e32 v223, v179, v223
	v_mul_f32_e32 v224, v180, v224
	v_mul_f32_e32 v225, v181, v225
	v_mul_f32_e32 v226, v182, v226
	v_mul_f32_e32 v227, v183, v227
	v_fma_f32 v220, v176, v220, v176
	v_fma_f32 v221, v177, v221, v177
	v_fma_f32 v222, v178, v222, v178
	v_fma_f32 v223, v179, v223, v179
	v_fma_f32 v224, v180, v224, v180
	v_fma_f32 v225, v181, v225, v181
	v_fma_f32 v226, v182, v226, v182
	v_fma_f32 v227, v183, v227, v183
	v_mul_f32_e32 v220, 0xbfcc422a, v220
	v_mul_f32_e32 v221, 0xbfcc422a, v221
	v_mul_f32_e32 v222, 0xbfcc422a, v222
	v_mul_f32_e32 v223, 0xbfcc422a, v223
	v_mul_f32_e32 v224, 0xbfcc422a, v224
	v_mul_f32_e32 v225, 0xbfcc422a, v225
	v_mul_f32_e32 v226, 0xbfcc422a, v226
	v_mul_f32_e32 v227, 0xbfcc422a, v227
	v_mul_f32_e32 v220, 0x3fb8aa3b, v220
	v_mul_f32_e32 v221, 0x3fb8aa3b, v221
	v_mul_f32_e32 v222, 0x3fb8aa3b, v222
	v_mul_f32_e32 v223, 0x3fb8aa3b, v223
	v_mul_f32_e32 v224, 0x3fb8aa3b, v224
	v_mul_f32_e32 v225, 0x3fb8aa3b, v225
	v_mul_f32_e32 v226, 0x3fb8aa3b, v226
	v_mul_f32_e32 v227, 0x3fb8aa3b, v227
	v_exp_f32_e32 v220, v220
	v_exp_f32_e32 v221, v221
	v_exp_f32_e32 v222, v222
	v_exp_f32_e32 v223, v223
	v_exp_f32_e32 v224, v224
	v_exp_f32_e32 v225, v225
	v_exp_f32_e32 v226, v226
	v_exp_f32_e32 v227, v227
	v_add_f32_e32 v220, 1.0, v220
	v_add_f32_e32 v221, 1.0, v221
	v_add_f32_e32 v222, 1.0, v222
	v_add_f32_e32 v223, 1.0, v223
	v_add_f32_e32 v224, 1.0, v224
	v_add_f32_e32 v225, 1.0, v225
	v_add_f32_e32 v226, 1.0, v226
	v_add_f32_e32 v227, 1.0, v227
	v_rcp_f32_e32 v220, v220
	v_rcp_f32_e32 v221, v221
	v_rcp_f32_e32 v222, v222
	v_rcp_f32_e32 v223, v223
	v_rcp_f32_e32 v224, v224
	v_rcp_f32_e32 v225, v225
	v_rcp_f32_e32 v226, v226
	v_rcp_f32_e32 v227, v227
	v_mul_f32_e32 v176, v176, v220
	v_mul_f32_e32 v177, v177, v221
	v_mul_f32_e32 v178, v178, v222
	v_mul_f32_e32 v179, v179, v223
	v_mul_f32_e32 v180, v180, v224
	v_mul_f32_e32 v181, v181, v225
	v_mul_f32_e32 v182, v182, v226
	v_mul_f32_e32 v183, v183, v227
	s_waitcnt lgkmcnt(2)
	v_mul_f32_e32 v176, v212, v176
	v_mul_f32_e32 v177, v213, v177
	v_mul_f32_e32 v178, v214, v178
	v_mul_f32_e32 v179, v215, v179
	v_mul_f32_e32 v180, v216, v180
	v_mul_f32_e32 v181, v217, v181
	v_mul_f32_e32 v182, v218, v182
	v_mul_f32_e32 v183, v219, v183
	v_mul_f32_e32 v176, v66, v176
	v_mul_f32_e32 v177, v66, v177
	v_mul_f32_e32 v178, v66, v178
	v_mul_f32_e32 v179, v66, v179
	v_mul_f32_e32 v180, v66, v180
	v_mul_f32_e32 v181, v66, v181
	v_mul_f32_e32 v182, v66, v182
	v_mul_f32_e32 v183, v66, v183
	v_bfe_u32 v220, v176, 16, 1
	v_bfe_u32 v221, v177, 16, 1
	v_bfe_u32 v222, v178, 16, 1
	v_bfe_u32 v223, v179, 16, 1
	v_bfe_u32 v224, v180, 16, 1
	v_bfe_u32 v225, v181, 16, 1
	v_bfe_u32 v226, v182, 16, 1
	v_bfe_u32 v227, v183, 16, 1
	v_add3_u32 v176, v176, v220, s89
	v_add3_u32 v177, v177, v221, s89
	v_add3_u32 v178, v178, v222, s89
	v_add3_u32 v179, v179, v223, s89
	v_add3_u32 v180, v180, v224, s89
	v_add3_u32 v181, v181, v225, s89
	v_add3_u32 v182, v182, v226, s89
	v_add3_u32 v183, v183, v227, s89
	v_lshrrev_b32_e32 v224, 16, v176
	v_lshrrev_b32_e32 v225, 16, v178
	v_lshrrev_b32_e32 v226, 16, v180
	v_lshrrev_b32_e32 v227, 16, v182
	v_and_or_b32 v220, v177, s75, v224
	v_and_or_b32 v221, v179, s75, v225
	v_and_or_b32 v222, v181, s75, v226
	v_and_or_b32 v223, v183, s75, v227
	ds_write_b128 v75, v[220:223] offset:80
	ds_read_b128 v[212:215], v200 offset:224
	ds_read_b128 v[216:219], v200 offset:240
	s_waitcnt vmcnt(8)
	v_mul_f32_e32 v220, 0x3d372713, v184
	v_mul_f32_e32 v221, 0x3d372713, v185
	v_mul_f32_e32 v222, 0x3d372713, v186
	v_mul_f32_e32 v223, 0x3d372713, v187
	v_mul_f32_e32 v224, 0x3d372713, v188
	v_mul_f32_e32 v225, 0x3d372713, v189
	v_mul_f32_e32 v226, 0x3d372713, v190
	v_mul_f32_e32 v227, 0x3d372713, v191
	v_mul_f32_e32 v220, v184, v220
	v_mul_f32_e32 v221, v185, v221
	v_mul_f32_e32 v222, v186, v222
	v_mul_f32_e32 v223, v187, v223
	v_mul_f32_e32 v224, v188, v224
	v_mul_f32_e32 v225, v189, v225
	v_mul_f32_e32 v226, v190, v226
	v_mul_f32_e32 v227, v191, v227
	v_fma_f32 v220, v184, v220, v184
	v_fma_f32 v221, v185, v221, v185
	v_fma_f32 v222, v186, v222, v186
	v_fma_f32 v223, v187, v223, v187
	v_fma_f32 v224, v188, v224, v188
	v_fma_f32 v225, v189, v225, v189
	v_fma_f32 v226, v190, v226, v190
	v_fma_f32 v227, v191, v227, v191
	v_mul_f32_e32 v220, 0xbfcc422a, v220
	v_mul_f32_e32 v221, 0xbfcc422a, v221
	v_mul_f32_e32 v222, 0xbfcc422a, v222
	v_mul_f32_e32 v223, 0xbfcc422a, v223
	v_mul_f32_e32 v224, 0xbfcc422a, v224
	v_mul_f32_e32 v225, 0xbfcc422a, v225
	v_mul_f32_e32 v226, 0xbfcc422a, v226
	v_mul_f32_e32 v227, 0xbfcc422a, v227
	v_mul_f32_e32 v220, 0x3fb8aa3b, v220
	v_mul_f32_e32 v221, 0x3fb8aa3b, v221
	v_mul_f32_e32 v222, 0x3fb8aa3b, v222
	v_mul_f32_e32 v223, 0x3fb8aa3b, v223
	v_mul_f32_e32 v224, 0x3fb8aa3b, v224
	v_mul_f32_e32 v225, 0x3fb8aa3b, v225
	v_mul_f32_e32 v226, 0x3fb8aa3b, v226
	v_mul_f32_e32 v227, 0x3fb8aa3b, v227
	v_exp_f32_e32 v220, v220
	v_exp_f32_e32 v221, v221
	v_exp_f32_e32 v222, v222
	v_exp_f32_e32 v223, v223
	v_exp_f32_e32 v224, v224
	v_exp_f32_e32 v225, v225
	v_exp_f32_e32 v226, v226
	v_exp_f32_e32 v227, v227
	v_add_f32_e32 v220, 1.0, v220
	v_add_f32_e32 v221, 1.0, v221
	v_add_f32_e32 v222, 1.0, v222
	v_add_f32_e32 v223, 1.0, v223
	v_add_f32_e32 v224, 1.0, v224
	v_add_f32_e32 v225, 1.0, v225
	v_add_f32_e32 v226, 1.0, v226
	v_add_f32_e32 v227, 1.0, v227
	v_rcp_f32_e32 v220, v220
	v_rcp_f32_e32 v221, v221
	v_rcp_f32_e32 v222, v222
	v_rcp_f32_e32 v223, v223
	v_rcp_f32_e32 v224, v224
	v_rcp_f32_e32 v225, v225
	v_rcp_f32_e32 v226, v226
	v_rcp_f32_e32 v227, v227
	v_mul_f32_e32 v184, v184, v220
	v_mul_f32_e32 v185, v185, v221
	v_mul_f32_e32 v186, v186, v222
	v_mul_f32_e32 v187, v187, v223
	v_mul_f32_e32 v188, v188, v224
	v_mul_f32_e32 v189, v189, v225
	v_mul_f32_e32 v190, v190, v226
	v_mul_f32_e32 v191, v191, v227
	s_waitcnt lgkmcnt(2)
	v_mul_f32_e32 v184, v204, v184
	v_mul_f32_e32 v185, v205, v185
	v_mul_f32_e32 v186, v206, v186
	v_mul_f32_e32 v187, v207, v187
	v_mul_f32_e32 v188, v208, v188
	v_mul_f32_e32 v189, v209, v189
	v_mul_f32_e32 v190, v210, v190
	v_mul_f32_e32 v191, v211, v191
	v_mul_f32_e32 v184, v66, v184
	v_mul_f32_e32 v185, v66, v185
	v_mul_f32_e32 v186, v66, v186
	v_mul_f32_e32 v187, v66, v187
	v_mul_f32_e32 v188, v66, v188
	v_mul_f32_e32 v189, v66, v189
	v_mul_f32_e32 v190, v66, v190
	v_mul_f32_e32 v191, v66, v191
	v_bfe_u32 v220, v184, 16, 1
	v_bfe_u32 v221, v185, 16, 1
	v_bfe_u32 v222, v186, 16, 1
	v_bfe_u32 v223, v187, 16, 1
	v_bfe_u32 v224, v188, 16, 1
	v_bfe_u32 v225, v189, 16, 1
	v_bfe_u32 v226, v190, 16, 1
	v_bfe_u32 v227, v191, 16, 1
	v_add3_u32 v184, v184, v220, s89
	v_add3_u32 v185, v185, v221, s89
	v_add3_u32 v186, v186, v222, s89
	v_add3_u32 v187, v187, v223, s89
	v_add3_u32 v188, v188, v224, s89
	v_add3_u32 v189, v189, v225, s89
	v_add3_u32 v190, v190, v226, s89
	v_add3_u32 v191, v191, v227, s89
	v_lshrrev_b32_e32 v224, 16, v184
	v_lshrrev_b32_e32 v225, 16, v186
	v_lshrrev_b32_e32 v226, 16, v188
	v_lshrrev_b32_e32 v227, 16, v190
	v_and_or_b32 v220, v185, s75, v224
	v_and_or_b32 v221, v187, s75, v225
	v_and_or_b32 v222, v189, s75, v226
	v_and_or_b32 v223, v191, s75, v227
	ds_write_b128 v75, v[220:223] offset:96
	s_waitcnt vmcnt(0)
	v_mul_f32_e32 v220, 0x3d372713, v192
	v_mul_f32_e32 v221, 0x3d372713, v193
	v_mul_f32_e32 v222, 0x3d372713, v194
	v_mul_f32_e32 v223, 0x3d372713, v195
	v_mul_f32_e32 v224, 0x3d372713, v196
	v_mul_f32_e32 v225, 0x3d372713, v197
	v_mul_f32_e32 v226, 0x3d372713, v198
	v_mul_f32_e32 v227, 0x3d372713, v199
	v_mul_f32_e32 v220, v192, v220
	v_mul_f32_e32 v221, v193, v221
	v_mul_f32_e32 v222, v194, v222
	v_mul_f32_e32 v223, v195, v223
	v_mul_f32_e32 v224, v196, v224
	v_mul_f32_e32 v225, v197, v225
	v_mul_f32_e32 v226, v198, v226
	v_mul_f32_e32 v227, v199, v227
	v_fma_f32 v220, v192, v220, v192
	v_fma_f32 v221, v193, v221, v193
	v_fma_f32 v222, v194, v222, v194
	v_fma_f32 v223, v195, v223, v195
	v_fma_f32 v224, v196, v224, v196
	v_fma_f32 v225, v197, v225, v197
	v_fma_f32 v226, v198, v226, v198
	v_fma_f32 v227, v199, v227, v199
	v_mul_f32_e32 v220, 0xbfcc422a, v220
	v_mul_f32_e32 v221, 0xbfcc422a, v221
	v_mul_f32_e32 v222, 0xbfcc422a, v222
	v_mul_f32_e32 v223, 0xbfcc422a, v223
	v_mul_f32_e32 v224, 0xbfcc422a, v224
	v_mul_f32_e32 v225, 0xbfcc422a, v225
	v_mul_f32_e32 v226, 0xbfcc422a, v226
	v_mul_f32_e32 v227, 0xbfcc422a, v227
	v_mul_f32_e32 v220, 0x3fb8aa3b, v220
	v_mul_f32_e32 v221, 0x3fb8aa3b, v221
	v_mul_f32_e32 v222, 0x3fb8aa3b, v222
	v_mul_f32_e32 v223, 0x3fb8aa3b, v223
	v_mul_f32_e32 v224, 0x3fb8aa3b, v224
	v_mul_f32_e32 v225, 0x3fb8aa3b, v225
	v_mul_f32_e32 v226, 0x3fb8aa3b, v226
	v_mul_f32_e32 v227, 0x3fb8aa3b, v227
	v_exp_f32_e32 v220, v220
	v_exp_f32_e32 v221, v221
	v_exp_f32_e32 v222, v222
	v_exp_f32_e32 v223, v223
	v_exp_f32_e32 v224, v224
	v_exp_f32_e32 v225, v225
	v_exp_f32_e32 v226, v226
	v_exp_f32_e32 v227, v227
	v_add_f32_e32 v220, 1.0, v220
	v_add_f32_e32 v221, 1.0, v221
	v_add_f32_e32 v222, 1.0, v222
	v_add_f32_e32 v223, 1.0, v223
	v_add_f32_e32 v224, 1.0, v224
	v_add_f32_e32 v225, 1.0, v225
	v_add_f32_e32 v226, 1.0, v226
	v_add_f32_e32 v227, 1.0, v227
	v_rcp_f32_e32 v220, v220
	v_rcp_f32_e32 v221, v221
	v_rcp_f32_e32 v222, v222
	v_rcp_f32_e32 v223, v223
	v_rcp_f32_e32 v224, v224
	v_rcp_f32_e32 v225, v225
	v_rcp_f32_e32 v226, v226
	v_rcp_f32_e32 v227, v227
	v_mul_f32_e32 v192, v192, v220
	v_mul_f32_e32 v193, v193, v221
	v_mul_f32_e32 v194, v194, v222
	v_mul_f32_e32 v195, v195, v223
	v_mul_f32_e32 v196, v196, v224
	v_mul_f32_e32 v197, v197, v225
	v_mul_f32_e32 v198, v198, v226
	v_mul_f32_e32 v199, v199, v227
	s_waitcnt lgkmcnt(0)
	v_mul_f32_e32 v192, v212, v192
	v_mul_f32_e32 v193, v213, v193
	v_mul_f32_e32 v194, v214, v194
	v_mul_f32_e32 v195, v215, v195
	v_mul_f32_e32 v196, v216, v196
	v_mul_f32_e32 v197, v217, v197
	v_mul_f32_e32 v198, v218, v198
	v_mul_f32_e32 v199, v219, v199
	v_mul_f32_e32 v192, v66, v192
	v_mul_f32_e32 v193, v66, v193
	v_mul_f32_e32 v194, v66, v194
	v_mul_f32_e32 v195, v66, v195
	v_mul_f32_e32 v196, v66, v196
	v_mul_f32_e32 v197, v66, v197
	v_mul_f32_e32 v198, v66, v198
	v_mul_f32_e32 v199, v66, v199
	v_bfe_u32 v220, v192, 16, 1
	v_bfe_u32 v221, v193, 16, 1
	v_bfe_u32 v222, v194, 16, 1
	v_bfe_u32 v223, v195, 16, 1
	v_bfe_u32 v224, v196, 16, 1
	v_bfe_u32 v225, v197, 16, 1
	v_bfe_u32 v226, v198, 16, 1
	v_bfe_u32 v227, v199, 16, 1
	v_add3_u32 v192, v192, v220, s89
	v_add3_u32 v193, v193, v221, s89
	v_add3_u32 v194, v194, v222, s89
	v_add3_u32 v195, v195, v223, s89
	v_add3_u32 v196, v196, v224, s89
	v_add3_u32 v197, v197, v225, s89
	v_add3_u32 v198, v198, v226, s89
	v_add3_u32 v199, v199, v227, s89
	v_lshrrev_b32_e32 v224, 16, v192
	v_lshrrev_b32_e32 v225, 16, v194
	v_lshrrev_b32_e32 v226, 16, v196
	v_lshrrev_b32_e32 v227, 16, v198
	v_and_or_b32 v220, v193, s75, v224
	v_and_or_b32 v221, v195, s75, v225
	v_and_or_b32 v222, v197, s75, v226
	v_and_or_b32 v223, v199, s75, v227
	ds_write_b128 v75, v[220:223] offset:112
	ds_read_b128 v[136:139], v69 offset:2560
	ds_read_b128 v[140:143], v69 offset:7168
	ds_read_b128 v[144:147], v69 offset:2592
	ds_read_b128 v[148:151], v69 offset:7200
	ds_read_b128 v[152:155], v69 offset:2624
	ds_read_b128 v[156:159], v69 offset:7232
	ds_read_b128 v[160:163], v69 offset:2656
	ds_read_b128 v[164:167], v69 offset:7264
	v_mov_b32_e32 v75, v229
	s_mov_b32 s0, 64
	s_mov_b64 s[4:5], 0
	s_waitcnt lgkmcnt(7)
	v_mfma_f32_32x32x16_bf16 v[48:63], v[136:139], v[106:109], v[48:63]
	s_waitcnt lgkmcnt(6)
	v_mfma_f32_32x32x16_bf16 v[32:47], v[140:143], v[106:109], v[32:47]
	v_mfma_f32_32x32x16_bf16 v[16:31], v[136:139], v[110:113], v[16:31]
	v_mfma_f32_32x32x16_bf16 v[0:15], v[140:143], v[110:113], v[0:15]
	s_waitcnt lgkmcnt(5)
	v_mfma_f32_32x32x16_bf16 v[48:63], v[144:147], v[114:117], v[48:63]
	s_waitcnt lgkmcnt(4)
	v_mfma_f32_32x32x16_bf16 v[32:47], v[148:151], v[114:117], v[32:47]
	v_mfma_f32_32x32x16_bf16 v[16:31], v[144:147], v[118:121], v[16:31]
	v_mfma_f32_32x32x16_bf16 v[0:15], v[148:151], v[118:121], v[0:15]
	s_waitcnt lgkmcnt(3)
	v_mfma_f32_32x32x16_bf16 v[48:63], v[152:155], v[122:125], v[48:63]
	s_waitcnt lgkmcnt(2)
	v_mfma_f32_32x32x16_bf16 v[32:47], v[156:159], v[122:125], v[32:47]
	v_mfma_f32_32x32x16_bf16 v[16:31], v[152:155], v[126:129], v[16:31]
	v_mfma_f32_32x32x16_bf16 v[0:15], v[156:159], v[126:129], v[0:15]
	s_waitcnt lgkmcnt(1)
	v_mfma_f32_32x32x16_bf16 v[48:63], v[160:163], v[130:133], v[48:63]
	s_waitcnt lgkmcnt(0)
	v_mfma_f32_32x32x16_bf16 v[32:47], v[164:167], v[130:133], v[32:47]
	v_mfma_f32_32x32x16_bf16 v[16:31], v[160:163], v[90:93], v[16:31]
	v_mfma_f32_32x32x16_bf16 v[0:15], v[164:167], v[90:93], v[0:15]
	s_and_b64 vcc, exec, s[2:3]
	s_cbranch_vccz .LBB0_849
	ds_read_b64 v[90:91], v229 offset:63688
	s_lshl_b32 s4, s6, 6
	s_add_i32 s0, s8, 0xfffffec0
	v_or_b32_e32 v228, s4, v104
	v_lshlrev_b32_e32 v92, 7, v64
	s_lshr_b32 s5, s0, 1
	v_or_b32_e32 v64, v92, v228
	s_lshl_b32 s0, s5, 18
	v_ashrrev_i32_e32 v65, 31, v64
	s_waitcnt lgkmcnt(0)
	v_lshl_add_u64 v[64:65], v[64:65], 2, v[90:91]
	v_lshl_or_b32 v94, v228, 11, s0
	v_mov_b32_e32 v95, v229
	flat_load_dword v96, v[64:65]
	v_lshl_add_u64 v[64:65], v[94:95], 2, v[84:85]
	v_lshl_add_u64 v[64:65], v[86:87], 2, v[64:65]
	v_mov_b32_e32 v69, v229
	v_lshl_add_u64 v[68:69], v[64:65], 0, v[68:69]
	v_add_co_u32_e32 v64, vcc, s43, v68
	v_lshl_add_u64 v[98:99], v[68:69], 0, s[70:71]
	s_nop 0
	v_addc_co_u32_e32 v65, vcc, 0, v69, vcc
	global_load_dwordx4 v[64:67], v[64:65], off offset:2048
	v_xor_b32_e32 v72, 32, v244
	global_load_dwordx4 v[68:71], v[98:99], off offset:32
	v_cmp_lt_i32_e32 vcc, v72, v100
	v_cmp_gt_u32_e64 s[2:3], 32, v102
	s_waitcnt vmcnt(0) lgkmcnt(0)
	v_pk_add_f32 v[48:49], v[48:49], v[96:97] op_sel_hi:[1,0]
	v_cndmask_b32_e32 v72, v244, v72, vcc
	v_lshlrev_b32_e32 v105, 2, v72
	global_load_dwordx4 v[72:75], v[98:99], off offset:64
	global_load_dwordx4 v[76:79], v[98:99], off offset:96
	global_load_dwordx4 v[80:83], v[98:99], off offset:224
	v_pk_add_f32 v[50:51], v[50:51], v[96:97] op_sel_hi:[1,0]
	v_pk_add_f32 v[52:53], v[52:53], v[96:97] op_sel_hi:[1,0]
	v_mul_f32_e32 v93, 0x3d372713, v64
	v_mul_f32_e32 v95, 0x3d372713, v65
	v_mul_f32_e32 v97, 0x3d372713, v66
	v_mul_f32_e32 v100, 0x3d372713, v67
	v_mul_f32_e32 v101, 0x3d372713, v68
	v_mul_f32_e32 v106, 0x3d372713, v69
	v_mul_f32_e32 v107, 0x3d372713, v70
	v_mul_f32_e32 v108, 0x3d372713, v71
	v_mul_f32_e32 v93, v64, v93
	v_mul_f32_e32 v95, v65, v95
	v_mul_f32_e32 v97, v66, v97
	v_mul_f32_e32 v100, v67, v100
	v_mul_f32_e32 v101, v68, v101
	v_mul_f32_e32 v106, v69, v106
	v_mul_f32_e32 v107, v70, v107
	v_mul_f32_e32 v108, v71, v108
	v_fma_f32 v93, v64, v93, v64
	v_fma_f32 v95, v65, v95, v65
	v_fma_f32 v97, v66, v97, v66
	v_fma_f32 v100, v67, v100, v67
	v_fma_f32 v101, v68, v101, v68
	v_fma_f32 v106, v69, v106, v69
	v_fma_f32 v107, v70, v107, v70
	v_fma_f32 v108, v71, v108, v71
	v_mul_f32_e32 v93, 0xbfcc422a, v93
	v_mul_f32_e32 v95, 0xbfcc422a, v95
	v_mul_f32_e32 v97, 0xbfcc422a, v97
	v_mul_f32_e32 v100, 0xbfcc422a, v100
	v_mul_f32_e32 v101, 0xbfcc422a, v101
	v_mul_f32_e32 v106, 0xbfcc422a, v106
	v_mul_f32_e32 v107, 0xbfcc422a, v107
	v_mul_f32_e32 v108, 0xbfcc422a, v108
	v_mul_f32_e32 v93, 0x3fb8aa3b, v93
	v_mul_f32_e32 v95, 0x3fb8aa3b, v95
	v_mul_f32_e32 v97, 0x3fb8aa3b, v97
	v_mul_f32_e32 v100, 0x3fb8aa3b, v100
	v_mul_f32_e32 v101, 0x3fb8aa3b, v101
	v_mul_f32_e32 v106, 0x3fb8aa3b, v106
	v_mul_f32_e32 v107, 0x3fb8aa3b, v107
	v_mul_f32_e32 v108, 0x3fb8aa3b, v108
	v_exp_f32_e32 v93, v93
	v_exp_f32_e32 v95, v95
	v_exp_f32_e32 v97, v97
	v_exp_f32_e32 v100, v100
	v_exp_f32_e32 v101, v101
	v_exp_f32_e32 v106, v106
	v_exp_f32_e32 v107, v107
	v_exp_f32_e32 v108, v108
	v_add_f32_e32 v93, 1.0, v93
	v_add_f32_e32 v95, 1.0, v95
	v_add_f32_e32 v97, 1.0, v97
	v_add_f32_e32 v109, 1.0, v100
	v_add_f32_e32 v110, 1.0, v101
	v_add_f32_e32 v111, 1.0, v106
	v_add_f32_e32 v112, 1.0, v107
	v_add_f32_e32 v113, 1.0, v108
	v_rcp_f32_e32 v100, v93
	v_rcp_f32_e32 v101, v95
	v_rcp_f32_e32 v106, v97
	v_rcp_f32_e32 v107, v109
	v_rcp_f32_e32 v108, v110
	v_rcp_f32_e32 v109, v111
	v_rcp_f32_e32 v110, v112
	v_rcp_f32_e32 v111, v113
	v_pk_mul_f32 v[64:65], v[64:65], v[100:101]
	v_pk_mul_f32 v[100:101], v[66:67], v[106:107]
	v_pk_mul_f32 v[106:107], v[68:69], v[108:109]
	v_pk_mul_f32 v[66:67], v[48:49], v[64:65]
	v_pk_mul_f32 v[64:65], v[50:51], v[100:101]
	v_pk_mul_f32 v[48:49], v[52:53], v[106:107]
	v_pk_mul_f32 v[50:51], v[70:71], v[110:111]
	v_pk_add_f32 v[52:53], v[54:55], v[96:97] op_sel_hi:[1,0]
	global_load_dwordx4 v[106:109], v[98:99], off offset:128
	v_pk_mul_f32 v[50:51], v[52:53], v[50:51]
	s_waitcnt vmcnt(3)
	v_mul_f32_e32 v52, 0x3d372713, v72
	v_mul_f32_e32 v53, 0x3d372713, v73
	v_mul_f32_e32 v54, 0x3d372713, v74
	v_mul_f32_e32 v52, v72, v52
	v_mul_f32_e32 v53, v73, v53
	v_mul_f32_e32 v54, v74, v54
	v_mul_f32_e32 v55, 0x3d372713, v75
	v_fma_f32 v52, v72, v52, v72
	v_fma_f32 v53, v73, v53, v73
	v_fma_f32 v54, v74, v54, v74
	v_mul_f32_e32 v55, v75, v55
	v_mul_f32_e32 v52, 0xbfcc422a, v52
	v_mul_f32_e32 v53, 0xbfcc422a, v53
	v_mul_f32_e32 v54, 0xbfcc422a, v54
	v_fma_f32 v55, v75, v55, v75
	v_mul_f32_e32 v52, 0x3fb8aa3b, v52
	v_mul_f32_e32 v53, 0x3fb8aa3b, v53
	v_mul_f32_e32 v54, 0x3fb8aa3b, v54
	v_mul_f32_e32 v55, 0xbfcc422a, v55
	v_exp_f32_e32 v52, v52
	v_exp_f32_e32 v53, v53
	v_exp_f32_e32 v54, v54
	v_mul_f32_e32 v55, 0x3fb8aa3b, v55
	v_exp_f32_e32 v55, v55
	v_add_f32_e32 v52, 1.0, v52
	v_add_f32_e32 v53, 1.0, v53
	v_add_f32_e32 v54, 1.0, v54
	v_rcp_f32_e32 v52, v52
	v_rcp_f32_e32 v53, v53
	v_rcp_f32_e32 v112, v54
	v_add_f32_e32 v54, 1.0, v55
	v_rcp_f32_e32 v113, v54
	v_pk_mul_f32 v[52:53], v[72:73], v[52:53]
	v_pk_add_f32 v[54:55], v[56:57], v[96:97] op_sel_hi:[1,0]
	v_pk_add_f32 v[56:57], v[58:59], v[96:97] op_sel_hi:[1,0]
	v_pk_mul_f32 v[54:55], v[54:55], v[52:53]
	v_pk_mul_f32 v[52:53], v[74:75], v[112:113]
	global_load_dwordx4 v[72:75], v[98:99], off offset:160
	v_pk_mul_f32 v[52:53], v[56:57], v[52:53]
	s_waitcnt vmcnt(3)
	v_mul_f32_e32 v56, 0x3d372713, v76
	v_mul_f32_e32 v57, 0x3d372713, v77
	v_mul_f32_e32 v58, 0x3d372713, v78
	v_mul_f32_e32 v56, v76, v56
	v_mul_f32_e32 v57, v77, v57
	v_mul_f32_e32 v58, v78, v58
	v_mul_f32_e32 v59, 0x3d372713, v79
	v_fma_f32 v56, v76, v56, v76
	v_fma_f32 v57, v77, v57, v77
	v_fma_f32 v58, v78, v58, v78
	v_mul_f32_e32 v59, v79, v59
	v_mul_f32_e32 v56, 0xbfcc422a, v56
	v_mul_f32_e32 v57, 0xbfcc422a, v57
	v_mul_f32_e32 v58, 0xbfcc422a, v58
	v_fma_f32 v59, v79, v59, v79
	v_mul_f32_e32 v56, 0x3fb8aa3b, v56
	v_mul_f32_e32 v57, 0x3fb8aa3b, v57
	v_mul_f32_e32 v58, 0x3fb8aa3b, v58
	v_mul_f32_e32 v59, 0xbfcc422a, v59
	v_exp_f32_e32 v56, v56
	v_exp_f32_e32 v57, v57
	v_exp_f32_e32 v58, v58
	v_mul_f32_e32 v59, 0x3fb8aa3b, v59
	v_exp_f32_e32 v59, v59
	v_add_f32_e32 v56, 1.0, v56
	v_add_f32_e32 v57, 1.0, v57
	v_add_f32_e32 v58, 1.0, v58
	v_rcp_f32_e32 v56, v56
	v_rcp_f32_e32 v57, v57
	v_rcp_f32_e32 v116, v58
	v_add_f32_e32 v58, 1.0, v59
	v_rcp_f32_e32 v117, v58
	v_pk_mul_f32 v[56:57], v[76:77], v[56:57]
	v_pk_add_f32 v[58:59], v[60:61], v[96:97] op_sel_hi:[1,0]
	v_pk_add_f32 v[60:61], v[62:63], v[96:97] op_sel_hi:[1,0]
	v_pk_mul_f32 v[58:59], v[58:59], v[56:57]
	v_pk_mul_f32 v[56:57], v[78:79], v[116:117]
	global_load_dwordx4 v[76:79], v[98:99], off offset:192
	v_pk_mul_f32 v[56:57], v[60:61], v[56:57]
	s_waitcnt vmcnt(2)
	v_mul_f32_e32 v60, 0x3d372713, v106
	v_mul_f32_e32 v61, 0x3d372713, v107
	v_mul_f32_e32 v93, 0x3d372713, v108
	v_mul_f32_e32 v60, v106, v60
	v_mul_f32_e32 v61, v107, v61
	v_mul_f32_e32 v93, v108, v93
	v_mul_f32_e32 v95, 0x3d372713, v109
	v_fma_f32 v60, v106, v60, v106
	v_fma_f32 v61, v107, v61, v107
	v_fma_f32 v93, v108, v93, v108
	v_mul_f32_e32 v95, v109, v95
	v_mul_f32_e32 v60, 0xbfcc422a, v60
	v_mul_f32_e32 v61, 0xbfcc422a, v61
	v_mul_f32_e32 v93, 0xbfcc422a, v93
	v_fma_f32 v95, v109, v95, v109
	v_mul_f32_e32 v60, 0x3fb8aa3b, v60
	v_mul_f32_e32 v61, 0x3fb8aa3b, v61
	v_mul_f32_e32 v93, 0x3fb8aa3b, v93
	v_mul_f32_e32 v95, 0xbfcc422a, v95
	v_exp_f32_e32 v60, v60
	v_exp_f32_e32 v61, v61
	v_exp_f32_e32 v93, v93
	v_mul_f32_e32 v95, 0x3fb8aa3b, v95
	v_exp_f32_e32 v95, v95
	v_add_f32_e32 v60, 1.0, v60
	v_add_f32_e32 v61, 1.0, v61
	v_add_f32_e32 v93, 1.0, v93
	v_rcp_f32_e32 v60, v60
	v_rcp_f32_e32 v61, v61
	v_rcp_f32_e32 v116, v93
	v_add_f32_e32 v93, 1.0, v95
	v_rcp_f32_e32 v117, v93
	v_pk_mul_f32 v[60:61], v[106:107], v[60:61]
	v_pk_add_f32 v[32:33], v[32:33], v[96:97] op_sel_hi:[1,0]
	v_pk_add_f32 v[34:35], v[34:35], v[96:97] op_sel_hi:[1,0]
	v_pk_mul_f32 v[60:61], v[32:33], v[60:61]
	v_pk_mul_f32 v[32:33], v[108:109], v[116:117]
	v_pk_add_f32 v[36:37], v[36:37], v[96:97] op_sel_hi:[1,0]
	v_pk_mul_f32 v[32:33], v[34:35], v[32:33]
	s_waitcnt vmcnt(1)
	v_mul_f32_e32 v34, 0x3d372713, v72
	v_mul_f32_e32 v35, 0x3d372713, v73
	v_mul_f32_e32 v93, 0x3d372713, v74
	v_mul_f32_e32 v34, v72, v34
	v_mul_f32_e32 v35, v73, v35
	v_mul_f32_e32 v93, v74, v93
	v_mul_f32_e32 v95, 0x3d372713, v75
	v_fma_f32 v34, v72, v34, v72
	v_fma_f32 v35, v73, v35, v73
	v_fma_f32 v93, v74, v93, v74
	v_mul_f32_e32 v95, v75, v95
	v_mul_f32_e32 v34, 0xbfcc422a, v34
	v_mul_f32_e32 v35, 0xbfcc422a, v35
	v_mul_f32_e32 v93, 0xbfcc422a, v93
	v_fma_f32 v95, v75, v95, v75
	v_mul_f32_e32 v34, 0x3fb8aa3b, v34
	v_mul_f32_e32 v35, 0x3fb8aa3b, v35
	v_mul_f32_e32 v93, 0x3fb8aa3b, v93
	v_mul_f32_e32 v95, 0xbfcc422a, v95
	v_exp_f32_e32 v34, v34
	v_exp_f32_e32 v35, v35
	v_exp_f32_e32 v93, v93
	v_mul_f32_e32 v95, 0x3fb8aa3b, v95
	v_exp_f32_e32 v95, v95
	v_add_f32_e32 v34, 1.0, v34
	v_add_f32_e32 v35, 1.0, v35
	v_add_f32_e32 v93, 1.0, v93
	v_rcp_f32_e32 v34, v34
	v_rcp_f32_e32 v35, v35
	v_rcp_f32_e32 v116, v93
	v_add_f32_e32 v93, 1.0, v95
	v_rcp_f32_e32 v117, v93
	v_pk_mul_f32 v[34:35], v[72:73], v[34:35]
	v_pk_add_f32 v[38:39], v[38:39], v[96:97] op_sel_hi:[1,0]
	v_pk_mul_f32 v[36:37], v[36:37], v[34:35]
	v_pk_mul_f32 v[34:35], v[74:75], v[116:117]
	v_pk_add_f32 v[40:41], v[40:41], v[96:97] op_sel_hi:[1,0]
	v_pk_mul_f32 v[34:35], v[38:39], v[34:35]
	v_pk_add_f32 v[42:43], v[42:43], v[96:97] op_sel_hi:[1,0]
	s_waitcnt vmcnt(0)
	v_mul_f32_e32 v38, 0x3d372713, v76
	v_mul_f32_e32 v39, 0x3d372713, v77
	v_mul_f32_e32 v93, 0x3d372713, v78
	v_mul_f32_e32 v38, v76, v38
	v_mul_f32_e32 v39, v77, v39
	v_mul_f32_e32 v93, v78, v93
	v_mul_f32_e32 v95, 0x3d372713, v79
	v_fma_f32 v38, v76, v38, v76
	v_fma_f32 v39, v77, v39, v77
	v_fma_f32 v93, v78, v93, v78
	v_mul_f32_e32 v95, v79, v95
	v_mul_f32_e32 v38, 0xbfcc422a, v38
	v_mul_f32_e32 v39, 0xbfcc422a, v39
	v_mul_f32_e32 v93, 0xbfcc422a, v93
	v_fma_f32 v95, v79, v95, v79
	v_mul_f32_e32 v38, 0x3fb8aa3b, v38
	v_mul_f32_e32 v39, 0x3fb8aa3b, v39
	v_mul_f32_e32 v93, 0x3fb8aa3b, v93
	v_mul_f32_e32 v95, 0xbfcc422a, v95
	v_exp_f32_e32 v38, v38
	v_exp_f32_e32 v39, v39
	v_exp_f32_e32 v93, v93
	v_mul_f32_e32 v95, 0x3fb8aa3b, v95
	v_exp_f32_e32 v95, v95
	v_add_f32_e32 v38, 1.0, v38
	v_add_f32_e32 v39, 1.0, v39
	v_add_f32_e32 v93, 1.0, v93
	v_rcp_f32_e32 v38, v38
	v_rcp_f32_e32 v39, v39
	v_rcp_f32_e32 v116, v93
	v_add_f32_e32 v93, 1.0, v95
	v_rcp_f32_e32 v117, v93
	v_pk_mul_f32 v[38:39], v[76:77], v[38:39]
	v_mul_f32_e32 v93, 0x3d372713, v82
	v_pk_mul_f32 v[40:41], v[40:41], v[38:39]
	v_pk_mul_f32 v[38:39], v[78:79], v[116:117]
	v_mul_f32_e32 v93, v82, v93
	v_pk_mul_f32 v[38:39], v[42:43], v[38:39]
	v_mul_f32_e32 v42, 0x3d372713, v80
	v_mul_f32_e32 v43, 0x3d372713, v81
	v_mul_f32_e32 v42, v80, v42
	v_mul_f32_e32 v43, v81, v43
	v_mul_f32_e32 v95, 0x3d372713, v83
	v_fma_f32 v42, v80, v42, v80
	v_fma_f32 v43, v81, v43, v81
	v_fma_f32 v93, v82, v93, v82
	v_mul_f32_e32 v95, v83, v95
	v_mul_f32_e32 v42, 0xbfcc422a, v42
	v_mul_f32_e32 v43, 0xbfcc422a, v43
	v_mul_f32_e32 v93, 0xbfcc422a, v93
	v_fma_f32 v95, v83, v95, v83
	v_mul_f32_e32 v42, 0x3fb8aa3b, v42
	v_mul_f32_e32 v43, 0x3fb8aa3b, v43
	v_mul_f32_e32 v93, 0x3fb8aa3b, v93
	v_mul_f32_e32 v95, 0xbfcc422a, v95
	v_exp_f32_e32 v42, v42
	v_exp_f32_e32 v43, v43
	v_exp_f32_e32 v93, v93
	v_mul_f32_e32 v95, 0x3fb8aa3b, v95
	v_exp_f32_e32 v95, v95
	v_add_f32_e32 v42, 1.0, v42
	v_add_f32_e32 v43, 1.0, v43
	v_add_f32_e32 v93, 1.0, v93
	v_rcp_f32_e32 v42, v42
	v_rcp_f32_e32 v43, v43
	v_rcp_f32_e32 v116, v93
	v_add_f32_e32 v93, 1.0, v95
	v_rcp_f32_e32 v117, v93
	v_pk_mul_f32 v[100:101], v[66:67], v[66:67]
	v_pk_mul_f32 v[42:43], v[80:81], v[42:43]
	v_pk_add_f32 v[44:45], v[44:45], v[96:97] op_sel_hi:[1,0]
	v_pk_mul_f32 v[68:69], v[64:65], v[64:65]
	v_pk_mul_f32 v[42:43], v[44:45], v[42:43]
	v_pk_mul_f32 v[44:45], v[82:83], v[116:117]
	v_add_f32_e32 v82, v100, v101
	v_pk_mul_f32 v[70:71], v[48:49], v[48:49]
	v_add_f32_e32 v68, v68, v82
	v_pk_mul_f32 v[110:111], v[50:51], v[50:51]
	v_add_f32_e32 v68, v69, v68
	v_add_f32_e32 v69, v70, v71
	v_add_f32_e32 v69, v110, v69
	v_pk_mul_f32 v[112:113], v[54:55], v[54:55]
	v_add_f32_e32 v69, v111, v69
	v_pk_mul_f32 v[114:115], v[52:53], v[52:53]
	v_pk_mul_f32 v[62:63], v[58:59], v[58:59]
	v_add_f32_e32 v68, v68, v69
	v_add_f32_e32 v69, v112, v113
	v_pk_mul_f32 v[98:99], v[56:57], v[56:57]
	v_pk_mul_f32 v[106:107], v[60:61], v[60:61]
	v_add_f32_e32 v69, v114, v69
	v_add_f32_e32 v62, v62, v63
	v_pk_mul_f32 v[108:109], v[32:33], v[32:33]
	v_add_f32_e32 v69, v115, v69
	v_add_f32_e32 v62, v98, v62
	v_add_f32_e32 v63, v106, v107
	v_add_f32_e32 v68, v68, v69
	v_add_f32_e32 v62, v99, v62
	v_add_f32_e32 v63, v108, v63
	v_pk_mul_f32 v[72:73], v[36:37], v[36:37]
	v_add_f32_e32 v62, v68, v62
	v_add_f32_e32 v63, v109, v63
	v_pk_mul_f32 v[74:75], v[34:35], v[34:35]
	v_add_f32_e32 v62, v62, v63
	v_add_f32_e32 v63, v72, v73
	v_add_f32_e32 v63, v74, v63
	v_pk_mul_f32 v[76:77], v[40:41], v[40:41]
	v_pk_add_f32 v[46:47], v[46:47], v[96:97] op_sel_hi:[1,0]
	v_add_f32_e32 v63, v75, v63
	v_pk_mul_f32 v[78:79], v[38:39], v[38:39]
	v_pk_mul_f32 v[44:45], v[46:47], v[44:45]
	v_pk_mul_f32 v[46:47], v[42:43], v[42:43]
	v_add_f32_e32 v62, v62, v63
	v_add_f32_e32 v63, v76, v77
	v_pk_mul_f32 v[80:81], v[44:45], v[44:45]
	v_add_f32_e32 v63, v78, v63
	v_add_f32_e32 v46, v46, v47
	v_add_f32_e32 v63, v79, v63
	v_add_f32_e32 v46, v80, v46
	v_add_f32_e32 v62, v62, v63
	v_add_f32_e32 v46, v81, v46
	v_add_f32_e32 v46, v62, v46
	ds_bpermute_b32 v47, v105, v46
	v_lshlrev_b32_e32 v106, 2, v104
	v_lshl_add_u32 v107, v86, 2, v106
	s_and_saveexec_b64 s[0:1], s[2:3]
	s_cbranch_execz .LBB0_854
	s_waitcnt lgkmcnt(0)
	v_add_f32_e32 v46, v46, v47
	ds_write_b32 v107, v46 offset:512

.LBB0_878:
	v_cmp_eq_u32_e32 vcc, 0, v18
	v_mov_b32_e32 v3, v229
	v_lshl_add_u64 v[2:3], v[2:3], 2, v[70:71]
	v_cndmask_b32_e64 v1, 31, 0, vcc
	v_or_b32_e32 v4, v1, v0
	v_lshl_add_u64 v[2:3], v[2:3], 0, v[228:229]
	v_mov_b32_e32 v75, v229
	v_ashrrev_i32_e32 v5, 31, v4
	v_lshl_add_u64 v[2:3], v[2:3], 0, v[74:75]
	v_cndmask_b32_e64 v192, 31, 0, vcc
	v_or_b32_e32 v192, v192, v0
	v_ashrrev_i32_e32 v193, 31, v192
	v_lshlrev_b64 v[192:193], 13, v[192:193]
	v_lshl_add_u64 v[192:193], v[2:3], 0, v[192:193]
	global_load_dword v160, v[192:193], off offset:2048
	v_cndmask_b32_e64 v192, 30, 1, vcc
	v_or_b32_e32 v192, v192, v0
	v_ashrrev_i32_e32 v193, 31, v192
	v_lshlrev_b64 v[192:193], 13, v[192:193]
	v_lshl_add_u64 v[192:193], v[2:3], 0, v[192:193]
	global_load_dword v161, v[192:193], off offset:2048
	v_cndmask_b32_e64 v192, 29, 2, vcc
	v_or_b32_e32 v192, v192, v0
	v_ashrrev_i32_e32 v193, 31, v192
	v_lshlrev_b64 v[192:193], 13, v[192:193]
	v_lshl_add_u64 v[192:193], v[2:3], 0, v[192:193]
	global_load_dword v162, v[192:193], off offset:2048
	v_cndmask_b32_e64 v192, 28, 3, vcc
	v_or_b32_e32 v192, v192, v0
	v_ashrrev_i32_e32 v193, 31, v192
	v_lshlrev_b64 v[192:193], 13, v[192:193]
	v_lshl_add_u64 v[192:193], v[2:3], 0, v[192:193]
	global_load_dword v163, v[192:193], off offset:2048
	v_cndmask_b32_e64 v192, 27, 4, vcc
	v_or_b32_e32 v192, v192, v0
	v_ashrrev_i32_e32 v193, 31, v192
	v_lshlrev_b64 v[192:193], 13, v[192:193]
	v_lshl_add_u64 v[192:193], v[2:3], 0, v[192:193]
	global_load_dword v164, v[192:193], off offset:2048
	v_cndmask_b32_e64 v192, 26, 5, vcc
	v_or_b32_e32 v192, v192, v0
	v_ashrrev_i32_e32 v193, 31, v192
	v_lshlrev_b64 v[192:193], 13, v[192:193]
	v_lshl_add_u64 v[192:193], v[2:3], 0, v[192:193]
	global_load_dword v165, v[192:193], off offset:2048
	v_cndmask_b32_e64 v192, 25, 6, vcc
	v_or_b32_e32 v192, v192, v0
	v_ashrrev_i32_e32 v193, 31, v192
	v_lshlrev_b64 v[192:193], 13, v[192:193]
	v_lshl_add_u64 v[192:193], v[2:3], 0, v[192:193]
	global_load_dword v166, v[192:193], off offset:2048
	v_cndmask_b32_e64 v192, 24, 7, vcc
	v_or_b32_e32 v192, v192, v0
	v_ashrrev_i32_e32 v193, 31, v192
	v_lshlrev_b64 v[192:193], 13, v[192:193]
	v_lshl_add_u64 v[192:193], v[2:3], 0, v[192:193]
	global_load_dword v167, v[192:193], off offset:2048
	v_cndmask_b32_e64 v192, 23, 8, vcc
	v_or_b32_e32 v192, v192, v0
	v_ashrrev_i32_e32 v193, 31, v192
	v_lshlrev_b64 v[192:193], 13, v[192:193]
	v_lshl_add_u64 v[192:193], v[2:3], 0, v[192:193]
	global_load_dword v168, v[192:193], off offset:2048
	v_cndmask_b32_e64 v192, 22, 9, vcc
	v_or_b32_e32 v192, v192, v0
	v_ashrrev_i32_e32 v193, 31, v192
	v_lshlrev_b64 v[192:193], 13, v[192:193]
	v_lshl_add_u64 v[192:193], v[2:3], 0, v[192:193]
	global_load_dword v169, v[192:193], off offset:2048
	v_cndmask_b32_e64 v192, 21, 10, vcc
	v_or_b32_e32 v192, v192, v0
	v_ashrrev_i32_e32 v193, 31, v192
	v_lshlrev_b64 v[192:193], 13, v[192:193]
	v_lshl_add_u64 v[192:193], v[2:3], 0, v[192:193]
	global_load_dword v170, v[192:193], off offset:2048
	v_cndmask_b32_e64 v192, 20, 11, vcc
	v_or_b32_e32 v192, v192, v0
	v_ashrrev_i32_e32 v193, 31, v192
	v_lshlrev_b64 v[192:193], 13, v[192:193]
	v_lshl_add_u64 v[192:193], v[2:3], 0, v[192:193]
	global_load_dword v171, v[192:193], off offset:2048
	v_cndmask_b32_e64 v192, 19, 12, vcc
	v_or_b32_e32 v192, v192, v0
	v_ashrrev_i32_e32 v193, 31, v192
	v_lshlrev_b64 v[192:193], 13, v[192:193]
	v_lshl_add_u64 v[192:193], v[2:3], 0, v[192:193]
	global_load_dword v172, v[192:193], off offset:2048
	v_cndmask_b32_e64 v192, 18, 13, vcc
	v_or_b32_e32 v192, v192, v0
	v_ashrrev_i32_e32 v193, 31, v192
	v_lshlrev_b64 v[192:193], 13, v[192:193]
	v_lshl_add_u64 v[192:193], v[2:3], 0, v[192:193]
	global_load_dword v173, v[192:193], off offset:2048
	v_cndmask_b32_e64 v192, 17, 14, vcc
	v_or_b32_e32 v192, v192, v0
	v_ashrrev_i32_e32 v193, 31, v192
	v_lshlrev_b64 v[192:193], 13, v[192:193]
	v_lshl_add_u64 v[192:193], v[2:3], 0, v[192:193]
	global_load_dword v174, v[192:193], off offset:2048
	v_cndmask_b32_e64 v192, 16, 15, vcc
	v_or_b32_e32 v192, v192, v0
	v_ashrrev_i32_e32 v193, 31, v192
	v_lshlrev_b64 v[192:193], 13, v[192:193]
	v_lshl_add_u64 v[192:193], v[2:3], 0, v[192:193]
	global_load_dword v175, v[192:193], off offset:2048
	v_cndmask_b32_e64 v192, 15, 16, vcc
	v_or_b32_e32 v192, v192, v0
	v_ashrrev_i32_e32 v193, 31, v192
	v_lshlrev_b64 v[192:193], 13, v[192:193]
	v_lshl_add_u64 v[192:193], v[2:3], 0, v[192:193]
	global_load_dword v176, v[192:193], off offset:2048
	v_cndmask_b32_e64 v192, 14, 17, vcc
	v_or_b32_e32 v192, v192, v0
	v_ashrrev_i32_e32 v193, 31, v192
	v_lshlrev_b64 v[192:193], 13, v[192:193]
	v_lshl_add_u64 v[192:193], v[2:3], 0, v[192:193]
	global_load_dword v177, v[192:193], off offset:2048
	v_cndmask_b32_e64 v192, 13, 18, vcc
	v_or_b32_e32 v192, v192, v0
	v_ashrrev_i32_e32 v193, 31, v192
	v_lshlrev_b64 v[192:193], 13, v[192:193]
	v_lshl_add_u64 v[192:193], v[2:3], 0, v[192:193]
	global_load_dword v178, v[192:193], off offset:2048
	v_cndmask_b32_e64 v192, 12, 19, vcc
	v_or_b32_e32 v192, v192, v0
	v_ashrrev_i32_e32 v193, 31, v192
	v_lshlrev_b64 v[192:193], 13, v[192:193]
	v_lshl_add_u64 v[192:193], v[2:3], 0, v[192:193]
	global_load_dword v179, v[192:193], off offset:2048
	v_cndmask_b32_e64 v192, 11, 20, vcc
	v_or_b32_e32 v192, v192, v0
	v_ashrrev_i32_e32 v193, 31, v192
	v_lshlrev_b64 v[192:193], 13, v[192:193]
	v_lshl_add_u64 v[192:193], v[2:3], 0, v[192:193]
	global_load_dword v180, v[192:193], off offset:2048
	v_cndmask_b32_e64 v192, 10, 21, vcc
	v_or_b32_e32 v192, v192, v0
	v_ashrrev_i32_e32 v193, 31, v192
	v_lshlrev_b64 v[192:193], 13, v[192:193]
	v_lshl_add_u64 v[192:193], v[2:3], 0, v[192:193]
	global_load_dword v181, v[192:193], off offset:2048
	v_cndmask_b32_e64 v192, 9, 22, vcc
	v_or_b32_e32 v192, v192, v0
	v_ashrrev_i32_e32 v193, 31, v192
	v_lshlrev_b64 v[192:193], 13, v[192:193]
	v_lshl_add_u64 v[192:193], v[2:3], 0, v[192:193]
	global_load_dword v182, v[192:193], off offset:2048
	v_cndmask_b32_e64 v192, 8, 23, vcc
	v_or_b32_e32 v192, v192, v0
	v_ashrrev_i32_e32 v193, 31, v192
	v_lshlrev_b64 v[192:193], 13, v[192:193]
	v_lshl_add_u64 v[192:193], v[2:3], 0, v[192:193]
	global_load_dword v183, v[192:193], off offset:2048
	v_cndmask_b32_e64 v192, 7, 24, vcc
	v_or_b32_e32 v192, v192, v0
	v_ashrrev_i32_e32 v193, 31, v192
	v_lshlrev_b64 v[192:193], 13, v[192:193]
	v_lshl_add_u64 v[192:193], v[2:3], 0, v[192:193]
	global_load_dword v184, v[192:193], off offset:2048
	v_cndmask_b32_e64 v192, 6, 25, vcc
	v_or_b32_e32 v192, v192, v0
	v_ashrrev_i32_e32 v193, 31, v192
	v_lshlrev_b64 v[192:193], 13, v[192:193]
	v_lshl_add_u64 v[192:193], v[2:3], 0, v[192:193]
	global_load_dword v185, v[192:193], off offset:2048
	v_cndmask_b32_e64 v192, 5, 26, vcc
	v_or_b32_e32 v192, v192, v0
	v_ashrrev_i32_e32 v193, 31, v192
	v_lshlrev_b64 v[192:193], 13, v[192:193]
	v_lshl_add_u64 v[192:193], v[2:3], 0, v[192:193]
	global_load_dword v186, v[192:193], off offset:2048
	v_cndmask_b32_e64 v192, 4, 27, vcc
	v_or_b32_e32 v192, v192, v0
	v_ashrrev_i32_e32 v193, 31, v192
	v_lshlrev_b64 v[192:193], 13, v[192:193]
	v_lshl_add_u64 v[192:193], v[2:3], 0, v[192:193]
	global_load_dword v187, v[192:193], off offset:2048
	v_cndmask_b32_e64 v192, 3, 28, vcc
	v_or_b32_e32 v192, v192, v0
	v_ashrrev_i32_e32 v193, 31, v192
	v_lshlrev_b64 v[192:193], 13, v[192:193]
	v_lshl_add_u64 v[192:193], v[2:3], 0, v[192:193]
	global_load_dword v188, v[192:193], off offset:2048
	v_cndmask_b32_e64 v192, 2, 29, vcc
	v_or_b32_e32 v192, v192, v0
	v_ashrrev_i32_e32 v193, 31, v192
	v_lshlrev_b64 v[192:193], 13, v[192:193]
	v_lshl_add_u64 v[192:193], v[2:3], 0, v[192:193]
	global_load_dword v189, v[192:193], off offset:2048
	v_cndmask_b32_e64 v192, 1, 30, vcc
	v_or_b32_e32 v192, v192, v0
	v_ashrrev_i32_e32 v193, 31, v192
	v_lshlrev_b64 v[192:193], 13, v[192:193]
	v_lshl_add_u64 v[192:193], v[2:3], 0, v[192:193]
	global_load_dword v190, v[192:193], off offset:2048
	v_cndmask_b32_e64 v192, 0, 31, vcc
	v_or_b32_e32 v192, v192, v0
	v_ashrrev_i32_e32 v193, 31, v192
	v_lshlrev_b64 v[192:193], 13, v[192:193]
	v_lshl_add_u64 v[192:193], v[2:3], 0, v[192:193]
	global_load_dword v191, v[192:193], off offset:2048
	v_lshlrev_b64 v[4:5], 13, v[4:5]
	v_lshl_add_u64 v[4:5], v[2:3], 0, v[4:5]
	v_cmp_neq_f32_e64 s[6:7], 0, v7
	s_waitcnt vmcnt(31)
	v_mov_b32_e32 v6, v160
	v_mul_f32_e64 v1, |v6|, s81
	v_exp_f32_e32 v5, v1
	v_sub_f32_e32 v1, 1.0, v7
	v_cmp_le_f32_e64 s[2:3], 0, v6
	v_add_f32_e32 v8, 1.0, v5
	v_rcp_f32_e32 v4, v8
	s_nop 0
	v_mul_f32_e32 v5, v5, v4
	s_and_saveexec_b64 s[0:1], s[6:7]
	s_xor_b64 s[8:9], exec, s[0:1]
	s_cbranch_execz .LBB0_880
	v_cndmask_b32_e64 v6, v5, v4, s[2:3]
	v_fma_f32 v6, v1, v6, v7
	v_cmp_gt_f32_e64 s[0:1], s92, v6
	s_nop 1
	v_cndmask_b32_e64 v8, 0, 32, s[0:1]
	v_ldexp_f32 v6, v6, v8
	v_log_f32_e32 v6, v6
	s_nop 0
	v_mul_f32_e32 v8, 0x3f317217, v6
	v_fma_f32 v8, v6, s96, -v8
	v_fmac_f32_e32 v8, 0x3377d1cf, v6
	v_fmac_f32_e32 v8, 0x3f317217, v6
	v_cmp_lt_f32_e64 s[4:5], |v6|, s33
	s_nop 1
	v_cndmask_b32_e64 v6, v6, v8, s[4:5]
	v_cndmask_b32_e64 v8, 0, v249, s[0:1]
	v_sub_f32_e32 v9, v6, v8

.LBB0_882:
	s_or_b64 exec, exec, s[8:9]
	v_cndmask_b32_e64 v6, 30, 1, vcc
	v_or_b32_e32 v10, v6, v0
	v_ashrrev_i32_e32 v11, 31, v10
	v_lshlrev_b64 v[10:11], 13, v[10:11]
	v_lshl_add_u64 v[10:11], v[2:3], 0, v[10:11]
	s_waitcnt vmcnt(30)
	v_mov_b32_e32 v10, v161
	v_mul_f32_e64 v6, |v10|, s81
	v_exp_f32_e32 v8, v6
	v_cmp_le_f32_e64 s[4:5], 0, v10
	v_add_f32_e32 v11, 1.0, v8
	v_rcp_f32_e32 v6, v11
	s_nop 0
	v_mul_f32_e32 v8, v8, v6
	s_and_saveexec_b64 s[0:1], s[6:7]
	s_xor_b64 s[10:11], exec, s[0:1]
	s_cbranch_execz .LBB0_884
	v_cndmask_b32_e64 v10, v8, v6, s[4:5]
	v_fma_f32 v10, v1, v10, v7
	v_cmp_gt_f32_e64 s[0:1], s92, v10
	s_nop 1
	v_cndmask_b32_e64 v11, 0, 32, s[0:1]
	v_ldexp_f32 v10, v10, v11
	v_log_f32_e32 v10, v10
	s_nop 0
	v_mul_f32_e32 v11, 0x3f317217, v10
	v_fma_f32 v11, v10, s96, -v11
	v_fmac_f32_e32 v11, 0x3377d1cf, v10
	v_fmac_f32_e32 v11, 0x3f317217, v10
	v_cmp_lt_f32_e64 s[8:9], |v10|, s33
	s_nop 1
	v_cndmask_b32_e64 v10, v10, v11, s[8:9]
	v_cndmask_b32_e64 v11, 0, v249, s[0:1]
	v_sub_f32_e32 v12, v10, v11

.LBB0_886:
	s_or_b64 exec, exec, s[10:11]
	v_cndmask_b32_e64 v10, 29, 2, vcc
	v_or_b32_e32 v10, v10, v0
	v_ashrrev_i32_e32 v11, 31, v10
	v_lshlrev_b64 v[10:11], 13, v[10:11]
	v_lshl_add_u64 v[10:11], v[2:3], 0, v[10:11]
	s_waitcnt vmcnt(29)
	v_mov_b32_e32 v13, v162
	v_mul_f32_e64 v10, |v13|, s81
	v_exp_f32_e32 v11, v10
	v_cmp_le_f32_e64 s[8:9], 0, v13
	v_add_f32_e32 v14, 1.0, v11
	v_rcp_f32_e32 v10, v14
	s_nop 0
	v_mul_f32_e32 v11, v11, v10
	s_and_saveexec_b64 s[0:1], s[6:7]
	s_xor_b64 s[12:13], exec, s[0:1]
	s_cbranch_execz .LBB0_888
	v_cndmask_b32_e64 v13, v11, v10, s[8:9]
	v_fma_f32 v13, v1, v13, v7
	v_cmp_gt_f32_e64 s[0:1], s92, v13
	s_nop 1
	v_cndmask_b32_e64 v14, 0, 32, s[0:1]
	v_ldexp_f32 v13, v13, v14
	v_log_f32_e32 v13, v13
	s_nop 0
	v_mul_f32_e32 v14, 0x3f317217, v13
	v_fma_f32 v14, v13, s96, -v14
	v_fmac_f32_e32 v14, 0x3377d1cf, v13
	v_fmac_f32_e32 v14, 0x3f317217, v13
	v_cmp_lt_f32_e64 s[10:11], |v13|, s33
	s_nop 1
	v_cndmask_b32_e64 v13, v13, v14, s[10:11]
	v_cndmask_b32_e64 v14, 0, v249, s[0:1]
	v_sub_f32_e32 v15, v13, v14

.LBB0_890:
	s_or_b64 exec, exec, s[12:13]
	v_cndmask_b32_e64 v13, 28, 3, vcc
	v_or_b32_e32 v16, v13, v0
	v_ashrrev_i32_e32 v17, 31, v16
	v_lshlrev_b64 v[16:17], 13, v[16:17]
	v_lshl_add_u64 v[16:17], v[2:3], 0, v[16:17]
	s_waitcnt vmcnt(28)
	v_mov_b32_e32 v16, v163
	v_mul_f32_e64 v13, |v16|, s81
	v_exp_f32_e32 v14, v13
	v_cmp_le_f32_e64 s[10:11], 0, v16
	v_add_f32_e32 v17, 1.0, v14
	v_rcp_f32_e32 v13, v17
	s_nop 0
	v_mul_f32_e32 v14, v14, v13
	s_and_saveexec_b64 s[0:1], s[6:7]
	s_xor_b64 s[14:15], exec, s[0:1]
	s_cbranch_execz .LBB0_892
	v_cndmask_b32_e64 v16, v14, v13, s[10:11]
	v_fma_f32 v16, v1, v16, v7
	v_cmp_gt_f32_e64 s[0:1], s92, v16
	s_nop 1
	v_cndmask_b32_e64 v17, 0, 32, s[0:1]
	v_ldexp_f32 v16, v16, v17
	v_log_f32_e32 v16, v16
	s_nop 0
	v_mul_f32_e32 v17, 0x3f317217, v16
	v_fma_f32 v17, v16, s96, -v17
	v_fmac_f32_e32 v17, 0x3377d1cf, v16
	v_fmac_f32_e32 v17, 0x3f317217, v16
	v_cmp_lt_f32_e64 s[12:13], |v16|, s33
	s_nop 1
	v_cndmask_b32_e64 v16, v16, v17, s[12:13]
	v_cndmask_b32_e64 v17, 0, v249, s[0:1]
	v_sub_f32_e32 v19, v16, v17

.LBB0_894:
	s_or_b64 exec, exec, s[14:15]
	v_cndmask_b32_e64 v16, 27, 4, vcc
	v_or_b32_e32 v16, v16, v0
	v_ashrrev_i32_e32 v17, 31, v16
	v_lshlrev_b64 v[16:17], 13, v[16:17]
	v_lshl_add_u64 v[16:17], v[2:3], 0, v[16:17]
	s_waitcnt vmcnt(27)
	v_mov_b32_e32 v20, v164
	v_mul_f32_e64 v16, |v20|, s81
	v_exp_f32_e32 v17, v16
	v_cmp_le_f32_e64 s[12:13], 0, v20
	v_add_f32_e32 v21, 1.0, v17
	v_rcp_f32_e32 v16, v21
	s_nop 0
	v_mul_f32_e32 v17, v17, v16
	s_and_saveexec_b64 s[0:1], s[6:7]
	s_xor_b64 s[16:17], exec, s[0:1]
	s_cbranch_execz .LBB0_896
	v_cndmask_b32_e64 v20, v17, v16, s[12:13]
	v_fma_f32 v20, v1, v20, v7
	v_cmp_gt_f32_e64 s[0:1], s92, v20
	s_nop 1
	v_cndmask_b32_e64 v21, 0, 32, s[0:1]
	v_ldexp_f32 v20, v20, v21
	v_log_f32_e32 v20, v20
	s_nop 0
	v_mul_f32_e32 v21, 0x3f317217, v20
	v_fma_f32 v21, v20, s96, -v21
	v_fmac_f32_e32 v21, 0x3377d1cf, v20
	v_fmac_f32_e32 v21, 0x3f317217, v20
	v_cmp_lt_f32_e64 s[14:15], |v20|, s33
	s_nop 1
	v_cndmask_b32_e64 v20, v20, v21, s[14:15]
	v_cndmask_b32_e64 v21, 0, v249, s[0:1]
	v_sub_f32_e32 v22, v20, v21

.LBB0_898:
	s_or_b64 exec, exec, s[16:17]
	v_cndmask_b32_e64 v20, 26, 5, vcc
	v_or_b32_e32 v20, v20, v0
	v_ashrrev_i32_e32 v21, 31, v20
	v_lshlrev_b64 v[20:21], 13, v[20:21]
	v_lshl_add_u64 v[20:21], v[2:3], 0, v[20:21]
	s_waitcnt vmcnt(26)
	v_mov_b32_e32 v23, v165
	v_mul_f32_e64 v20, |v23|, s81
	v_exp_f32_e32 v21, v20
	v_cmp_le_f32_e64 s[14:15], 0, v23
	v_add_f32_e32 v24, 1.0, v21
	v_rcp_f32_e32 v20, v24
	s_nop 0
	v_mul_f32_e32 v21, v21, v20
	s_and_saveexec_b64 s[0:1], s[6:7]
	s_xor_b64 s[18:19], exec, s[0:1]
	s_cbranch_execz .LBB0_900
	v_cndmask_b32_e64 v23, v21, v20, s[14:15]
	v_fma_f32 v23, v1, v23, v7
	v_cmp_gt_f32_e64 s[0:1], s92, v23
	s_nop 1
	v_cndmask_b32_e64 v24, 0, 32, s[0:1]
	v_ldexp_f32 v23, v23, v24
	v_log_f32_e32 v23, v23
	s_nop 0
	v_mul_f32_e32 v24, 0x3f317217, v23
	v_fma_f32 v24, v23, s96, -v24
	v_fmac_f32_e32 v24, 0x3377d1cf, v23
	v_fmac_f32_e32 v24, 0x3f317217, v23
	v_cmp_lt_f32_e64 s[16:17], |v23|, s33
	s_nop 1
	v_cndmask_b32_e64 v23, v23, v24, s[16:17]
	v_cndmask_b32_e64 v24, 0, v249, s[0:1]
	v_sub_f32_e32 v25, v23, v24

.LBB0_902:
	s_or_b64 exec, exec, s[18:19]
	v_cndmask_b32_e64 v23, 25, 6, vcc
	v_or_b32_e32 v26, v23, v0
	v_ashrrev_i32_e32 v27, 31, v26
	v_lshlrev_b64 v[26:27], 13, v[26:27]
	v_lshl_add_u64 v[26:27], v[2:3], 0, v[26:27]
	s_waitcnt vmcnt(25)
	v_mov_b32_e32 v26, v166
	v_mul_f32_e64 v23, |v26|, s81
	v_exp_f32_e32 v24, v23
	v_cmp_le_f32_e64 s[16:17], 0, v26
	v_add_f32_e32 v27, 1.0, v24
	v_rcp_f32_e32 v23, v27
	s_nop 0
	v_mul_f32_e32 v24, v24, v23
	s_and_saveexec_b64 s[0:1], s[6:7]
	s_xor_b64 s[20:21], exec, s[0:1]
	s_cbranch_execz .LBB0_904
	v_cndmask_b32_e64 v26, v24, v23, s[16:17]
	v_fma_f32 v26, v1, v26, v7
	v_cmp_gt_f32_e64 s[0:1], s92, v26
	s_nop 1
	v_cndmask_b32_e64 v27, 0, 32, s[0:1]
	v_ldexp_f32 v26, v26, v27
	v_log_f32_e32 v26, v26
	s_nop 0
	v_mul_f32_e32 v27, 0x3f317217, v26
	v_fma_f32 v27, v26, s96, -v27
	v_fmac_f32_e32 v27, 0x3377d1cf, v26
	v_fmac_f32_e32 v27, 0x3f317217, v26
	v_cmp_lt_f32_e64 s[18:19], |v26|, s33
	s_nop 1
	v_cndmask_b32_e64 v26, v26, v27, s[18:19]
	v_cndmask_b32_e64 v27, 0, v249, s[0:1]
	v_sub_f32_e32 v28, v26, v27

.LBB0_906:
	s_or_b64 exec, exec, s[20:21]
	v_cndmask_b32_e64 v26, 24, 7, vcc
	v_or_b32_e32 v26, v26, v0
	v_ashrrev_i32_e32 v27, 31, v26
	v_lshlrev_b64 v[26:27], 13, v[26:27]
	v_lshl_add_u64 v[26:27], v[2:3], 0, v[26:27]
	s_waitcnt vmcnt(24)
	v_mov_b32_e32 v29, v167
	v_mul_f32_e64 v26, |v29|, s81
	v_exp_f32_e32 v27, v26
	v_cmp_le_f32_e64 s[18:19], 0, v29
	v_add_f32_e32 v30, 1.0, v27
	v_rcp_f32_e32 v26, v30
	s_nop 0
	v_mul_f32_e32 v27, v27, v26
	s_and_saveexec_b64 s[0:1], s[6:7]
	s_xor_b64 s[22:23], exec, s[0:1]
	s_cbranch_execz .LBB0_908
	v_cndmask_b32_e64 v29, v27, v26, s[18:19]
	v_fma_f32 v29, v1, v29, v7
	v_cmp_gt_f32_e64 s[0:1], s92, v29
	s_nop 1
	v_cndmask_b32_e64 v30, 0, 32, s[0:1]
	v_ldexp_f32 v29, v29, v30
	v_log_f32_e32 v29, v29
	s_nop 0
	v_mul_f32_e32 v30, 0x3f317217, v29
	v_fma_f32 v30, v29, s96, -v30
	v_fmac_f32_e32 v30, 0x3377d1cf, v29
	v_fmac_f32_e32 v30, 0x3f317217, v29
	v_cmp_lt_f32_e64 s[20:21], |v29|, s33
	s_nop 1
	v_cndmask_b32_e64 v29, v29, v30, s[20:21]
	v_cndmask_b32_e64 v30, 0, v249, s[0:1]
	v_sub_f32_e32 v31, v29, v30

.LBB0_910:
	s_or_b64 exec, exec, s[22:23]
	v_cndmask_b32_e64 v29, 23, 8, vcc
	v_or_b32_e32 v32, v29, v0
	v_ashrrev_i32_e32 v33, 31, v32
	v_lshlrev_b64 v[32:33], 13, v[32:33]
	v_lshl_add_u64 v[32:33], v[2:3], 0, v[32:33]
	s_waitcnt vmcnt(23)
	v_mov_b32_e32 v32, v168
	v_mul_f32_e64 v29, |v32|, s81
	v_exp_f32_e32 v30, v29
	v_cmp_le_f32_e64 s[20:21], 0, v32
	v_add_f32_e32 v33, 1.0, v30
	v_rcp_f32_e32 v29, v33
	s_nop 0
	v_mul_f32_e32 v30, v30, v29
	s_and_saveexec_b64 s[0:1], s[6:7]
	s_xor_b64 s[24:25], exec, s[0:1]
	s_cbranch_execz .LBB0_912
	v_cndmask_b32_e64 v32, v30, v29, s[20:21]
	v_fma_f32 v32, v1, v32, v7
	v_cmp_gt_f32_e64 s[0:1], s92, v32
	s_nop 1
	v_cndmask_b32_e64 v33, 0, 32, s[0:1]
	v_ldexp_f32 v32, v32, v33
	v_log_f32_e32 v32, v32
	s_nop 0
	v_mul_f32_e32 v33, 0x3f317217, v32
	v_fma_f32 v33, v32, s96, -v33
	v_fmac_f32_e32 v33, 0x3377d1cf, v32
	v_fmac_f32_e32 v33, 0x3f317217, v32
	v_cmp_lt_f32_e64 s[22:23], |v32|, s33
	s_nop 1
	v_cndmask_b32_e64 v32, v32, v33, s[22:23]
	v_cndmask_b32_e64 v33, 0, v249, s[0:1]
	v_sub_f32_e32 v34, v32, v33

.LBB0_914:
	s_or_b64 exec, exec, s[24:25]
	v_cndmask_b32_e64 v32, 22, 9, vcc
	v_or_b32_e32 v32, v32, v0
	v_ashrrev_i32_e32 v33, 31, v32
	v_lshlrev_b64 v[32:33], 13, v[32:33]
	v_lshl_add_u64 v[32:33], v[2:3], 0, v[32:33]
	s_waitcnt vmcnt(22)
	v_mov_b32_e32 v35, v169
	v_mul_f32_e64 v32, |v35|, s81
	v_exp_f32_e32 v33, v32
	v_cmp_le_f32_e64 s[22:23], 0, v35
	v_add_f32_e32 v36, 1.0, v33
	v_rcp_f32_e32 v32, v36
	s_nop 0
	v_mul_f32_e32 v33, v33, v32
	s_and_saveexec_b64 s[0:1], s[6:7]
	s_xor_b64 s[26:27], exec, s[0:1]
	s_cbranch_execz .LBB0_916
	v_cndmask_b32_e64 v35, v33, v32, s[22:23]
	v_fma_f32 v35, v1, v35, v7
	v_cmp_gt_f32_e64 s[0:1], s92, v35
	s_nop 1
	v_cndmask_b32_e64 v36, 0, 32, s[0:1]
	v_ldexp_f32 v35, v35, v36
	v_log_f32_e32 v35, v35
	s_nop 0
	v_mul_f32_e32 v36, 0x3f317217, v35
	v_fma_f32 v36, v35, s96, -v36
	v_fmac_f32_e32 v36, 0x3377d1cf, v35
	v_fmac_f32_e32 v36, 0x3f317217, v35
	v_cmp_lt_f32_e64 s[24:25], |v35|, s33
	s_nop 1
	v_cndmask_b32_e64 v35, v35, v36, s[24:25]
	v_cndmask_b32_e64 v36, 0, v249, s[0:1]
	v_sub_f32_e32 v37, v35, v36

.LBB0_918:
	s_or_b64 exec, exec, s[26:27]
	v_cndmask_b32_e64 v35, 21, 10, vcc
	v_or_b32_e32 v38, v35, v0
	v_ashrrev_i32_e32 v39, 31, v38
	v_lshlrev_b64 v[38:39], 13, v[38:39]
	v_lshl_add_u64 v[38:39], v[2:3], 0, v[38:39]
	s_waitcnt vmcnt(21)
	v_mov_b32_e32 v38, v170
	v_mul_f32_e64 v35, |v38|, s81
	v_exp_f32_e32 v36, v35
	v_cmp_le_f32_e64 s[24:25], 0, v38
	v_add_f32_e32 v39, 1.0, v36
	v_rcp_f32_e32 v35, v39
	s_nop 0
	v_mul_f32_e32 v36, v36, v35
	s_and_saveexec_b64 s[0:1], s[6:7]
	s_xor_b64 s[28:29], exec, s[0:1]
	s_cbranch_execz .LBB0_920
	v_cndmask_b32_e64 v38, v36, v35, s[24:25]
	v_fma_f32 v38, v1, v38, v7
	v_cmp_gt_f32_e64 s[0:1], s92, v38
	s_nop 1
	v_cndmask_b32_e64 v39, 0, 32, s[0:1]
	v_ldexp_f32 v38, v38, v39
	v_log_f32_e32 v38, v38
	s_nop 0
	v_mul_f32_e32 v39, 0x3f317217, v38
	v_fma_f32 v39, v38, s96, -v39
	v_fmac_f32_e32 v39, 0x3377d1cf, v38
	v_fmac_f32_e32 v39, 0x3f317217, v38
	v_cmp_lt_f32_e64 s[26:27], |v38|, s33
	s_nop 1
	v_cndmask_b32_e64 v38, v38, v39, s[26:27]
	v_cndmask_b32_e64 v39, 0, v249, s[0:1]
	v_sub_f32_e32 v40, v38, v39

.LBB0_922:
	s_or_b64 exec, exec, s[28:29]
	v_cndmask_b32_e64 v38, 20, 11, vcc
	v_or_b32_e32 v38, v38, v0
	v_ashrrev_i32_e32 v39, 31, v38
	v_lshlrev_b64 v[38:39], 13, v[38:39]
	v_lshl_add_u64 v[38:39], v[2:3], 0, v[38:39]
	s_waitcnt vmcnt(20)
	v_mov_b32_e32 v41, v171
	v_mul_f32_e64 v38, |v41|, s81
	v_exp_f32_e32 v39, v38
	v_cmp_le_f32_e64 s[26:27], 0, v41
	v_add_f32_e32 v42, 1.0, v39
	v_rcp_f32_e32 v38, v42
	s_nop 0
	v_mul_f32_e32 v39, v39, v38
	s_and_saveexec_b64 s[0:1], s[6:7]
	s_xor_b64 s[30:31], exec, s[0:1]
	s_cbranch_execz .LBB0_924
	v_cndmask_b32_e64 v41, v39, v38, s[26:27]
	v_fma_f32 v41, v1, v41, v7
	v_cmp_gt_f32_e64 s[0:1], s92, v41
	s_nop 1
	v_cndmask_b32_e64 v42, 0, 32, s[0:1]
	v_ldexp_f32 v41, v41, v42
	v_log_f32_e32 v41, v41
	s_nop 0
	v_mul_f32_e32 v42, 0x3f317217, v41
	v_fma_f32 v42, v41, s96, -v42
	v_fmac_f32_e32 v42, 0x3377d1cf, v41
	v_fmac_f32_e32 v42, 0x3f317217, v41
	v_cmp_lt_f32_e64 s[28:29], |v41|, s33
	s_nop 1
	v_cndmask_b32_e64 v41, v41, v42, s[28:29]
	v_cndmask_b32_e64 v42, 0, v249, s[0:1]
	v_sub_f32_e32 v43, v41, v42

.LBB0_926:
	s_or_b64 exec, exec, s[30:31]
	v_cndmask_b32_e64 v41, 19, 12, vcc
	v_or_b32_e32 v44, v41, v0
	v_ashrrev_i32_e32 v45, 31, v44
	v_lshlrev_b64 v[44:45], 13, v[44:45]
	v_lshl_add_u64 v[44:45], v[2:3], 0, v[44:45]
	s_waitcnt vmcnt(19)
	v_mov_b32_e32 v44, v172
	v_mul_f32_e64 v41, |v44|, s81
	v_exp_f32_e32 v42, v41
	v_cmp_le_f32_e64 s[28:29], 0, v44
	v_add_f32_e32 v45, 1.0, v42
	v_rcp_f32_e32 v41, v45
	s_nop 0
	v_mul_f32_e32 v42, v42, v41
	s_and_saveexec_b64 s[0:1], s[6:7]
	s_xor_b64 s[34:35], exec, s[0:1]
	s_cbranch_execz .LBB0_928
	v_cndmask_b32_e64 v44, v42, v41, s[28:29]
	v_fma_f32 v44, v1, v44, v7
	v_cmp_gt_f32_e64 s[0:1], s92, v44
	s_nop 1
	v_cndmask_b32_e64 v45, 0, 32, s[0:1]
	v_ldexp_f32 v44, v44, v45
	v_log_f32_e32 v44, v44
	s_nop 0
	v_mul_f32_e32 v45, 0x3f317217, v44
	v_fma_f32 v45, v44, s96, -v45
	v_fmac_f32_e32 v45, 0x3377d1cf, v44
	v_fmac_f32_e32 v45, 0x3f317217, v44
	v_cmp_lt_f32_e64 s[30:31], |v44|, s33
	s_nop 1
	v_cndmask_b32_e64 v44, v44, v45, s[30:31]
	v_cndmask_b32_e64 v45, 0, v249, s[0:1]
	v_sub_f32_e32 v46, v44, v45

.LBB0_930:
	s_or_b64 exec, exec, s[34:35]
	v_cndmask_b32_e64 v44, 18, 13, vcc
	v_or_b32_e32 v44, v44, v0
	v_ashrrev_i32_e32 v45, 31, v44
	v_lshlrev_b64 v[44:45], 13, v[44:45]
	v_lshl_add_u64 v[44:45], v[2:3], 0, v[44:45]
	s_waitcnt vmcnt(18)
	v_mov_b32_e32 v47, v173
	v_mul_f32_e64 v44, |v47|, s81
	v_exp_f32_e32 v45, v44
	v_cmp_le_f32_e64 s[30:31], 0, v47
	v_add_f32_e32 v48, 1.0, v45
	v_rcp_f32_e32 v44, v48
	s_nop 0
	v_mul_f32_e32 v45, v45, v44
	s_and_saveexec_b64 s[0:1], s[6:7]
	s_xor_b64 s[36:37], exec, s[0:1]
	s_cbranch_execz .LBB0_932
	v_cndmask_b32_e64 v47, v45, v44, s[30:31]
	v_fma_f32 v47, v1, v47, v7
	v_cmp_gt_f32_e64 s[0:1], s92, v47
	s_nop 1
	v_cndmask_b32_e64 v48, 0, 32, s[0:1]
	v_ldexp_f32 v47, v47, v48
	v_log_f32_e32 v47, v47
	s_nop 0
	v_mul_f32_e32 v48, 0x3f317217, v47
	v_fma_f32 v48, v47, s96, -v48
	v_fmac_f32_e32 v48, 0x3377d1cf, v47
	v_fmac_f32_e32 v48, 0x3f317217, v47
	v_cmp_lt_f32_e64 s[34:35], |v47|, s33
	s_nop 1
	v_cndmask_b32_e64 v47, v47, v48, s[34:35]
	v_cndmask_b32_e64 v48, 0, v249, s[0:1]
	v_sub_f32_e32 v49, v47, v48

.LBB0_934:
	s_or_b64 exec, exec, s[36:37]
	v_cndmask_b32_e64 v47, 17, 14, vcc
	v_or_b32_e32 v50, v47, v0
	v_ashrrev_i32_e32 v51, 31, v50
	v_lshlrev_b64 v[50:51], 13, v[50:51]
	v_lshl_add_u64 v[50:51], v[2:3], 0, v[50:51]
	s_waitcnt vmcnt(17)
	v_mov_b32_e32 v50, v174
	v_mul_f32_e64 v47, |v50|, s81
	v_exp_f32_e32 v48, v47
	v_cmp_le_f32_e64 s[34:35], 0, v50
	v_add_f32_e32 v51, 1.0, v48
	v_rcp_f32_e32 v47, v51
	s_nop 0
	v_mul_f32_e32 v48, v48, v47
	s_and_saveexec_b64 s[0:1], s[6:7]
	s_xor_b64 s[38:39], exec, s[0:1]
	s_cbranch_execz .LBB0_936
	v_cndmask_b32_e64 v50, v48, v47, s[34:35]
	v_fma_f32 v50, v1, v50, v7
	v_cmp_gt_f32_e64 s[0:1], s92, v50
	s_nop 1
	v_cndmask_b32_e64 v51, 0, 32, s[0:1]
	v_ldexp_f32 v50, v50, v51
	v_log_f32_e32 v50, v50
	s_nop 0
	v_mul_f32_e32 v51, 0x3f317217, v50
	v_fma_f32 v51, v50, s96, -v51
	v_fmac_f32_e32 v51, 0x3377d1cf, v50
	v_fmac_f32_e32 v51, 0x3f317217, v50
	v_cmp_lt_f32_e64 s[36:37], |v50|, s33
	s_nop 1
	v_cndmask_b32_e64 v50, v50, v51, s[36:37]
	v_cndmask_b32_e64 v51, 0, v249, s[0:1]
	v_sub_f32_e32 v52, v50, v51

.LBB0_938:
	s_or_b64 exec, exec, s[38:39]
	v_add3_u32 v50, v18, v0, 15
	v_ashrrev_i32_e32 v51, 31, v50
	v_lshlrev_b64 v[50:51], 13, v[50:51]
	v_lshl_add_u64 v[50:51], v[2:3], 0, v[50:51]
	s_waitcnt vmcnt(16)
	v_mov_b32_e32 v53, v175
	v_mul_f32_e64 v50, |v53|, s81
	v_exp_f32_e32 v51, v50
	v_cmp_le_f32_e64 s[36:37], 0, v53
	v_add_f32_e32 v55, 1.0, v51
	v_rcp_f32_e32 v50, v55
	s_nop 0
	v_mul_f32_e32 v51, v51, v50
	s_and_saveexec_b64 s[0:1], s[6:7]
	s_xor_b64 s[40:41], exec, s[0:1]
	s_cbranch_execz .LBB0_940
	v_cndmask_b32_e64 v53, v51, v50, s[36:37]
	v_fma_f32 v53, v1, v53, v7
	v_cmp_gt_f32_e64 s[0:1], s92, v53
	s_nop 1
	v_cndmask_b32_e64 v54, 0, 32, s[0:1]
	v_ldexp_f32 v53, v53, v54
	v_log_f32_e32 v53, v53
	s_nop 0
	v_mul_f32_e32 v54, 0x3f317217, v53
	v_fma_f32 v54, v53, s96, -v54
	v_fmac_f32_e32 v54, 0x3377d1cf, v53
	v_fmac_f32_e32 v54, 0x3f317217, v53
	v_cmp_lt_f32_e64 s[38:39], |v53|, s33
	s_nop 1
	v_cndmask_b32_e64 v53, v53, v54, s[38:39]
	v_cndmask_b32_e64 v54, 0, v249, s[0:1]
	v_sub_f32_e32 v54, v53, v54

.LBB0_942:
	s_or_b64 exec, exec, s[40:41]
	v_sub_u32_e32 v18, v0, v18
	v_add_u32_e32 v56, 16, v18
	v_ashrrev_i32_e32 v57, 31, v56
	v_lshlrev_b64 v[56:57], 13, v[56:57]
	v_lshl_add_u64 v[56:57], v[2:3], 0, v[56:57]
	s_waitcnt vmcnt(15)
	v_mov_b32_e32 v55, v176
	v_mul_f32_e64 v18, |v55|, s81
	v_exp_f32_e32 v53, v18
	v_cmp_le_f32_e64 s[38:39], 0, v55
	v_add_f32_e32 v56, 1.0, v53
	v_rcp_f32_e32 v18, v56
	s_nop 0
	v_mul_f32_e32 v53, v53, v18
	s_and_saveexec_b64 s[0:1], s[6:7]
	s_xor_b64 s[42:43], exec, s[0:1]
	s_cbranch_execz .LBB0_944
	v_cndmask_b32_e64 v55, v53, v18, s[38:39]
	v_fma_f32 v55, v1, v55, v7
	v_cmp_gt_f32_e64 s[0:1], s92, v55
	s_nop 1
	v_cndmask_b32_e64 v56, 0, 32, s[0:1]
	v_ldexp_f32 v55, v55, v56
	v_log_f32_e32 v55, v55
	s_nop 0
	v_mul_f32_e32 v56, 0x3f317217, v55
	v_fma_f32 v56, v55, s96, -v56
	v_fmac_f32_e32 v56, 0x3377d1cf, v55
	v_fmac_f32_e32 v56, 0x3f317217, v55
	v_cmp_lt_f32_e64 s[40:41], |v55|, s33
	s_nop 1
	v_cndmask_b32_e64 v55, v55, v56, s[40:41]
	v_cndmask_b32_e64 v56, 0, v249, s[0:1]
	v_sub_f32_e32 v57, v55, v56

.LBB0_946:
	s_or_b64 exec, exec, s[42:43]
	v_cndmask_b32_e64 v55, 14, 17, vcc
	v_or_b32_e32 v58, v55, v0
	v_ashrrev_i32_e32 v59, 31, v58
	v_lshlrev_b64 v[58:59], 13, v[58:59]
	v_lshl_add_u64 v[58:59], v[2:3], 0, v[58:59]
	s_waitcnt vmcnt(14)
	v_mov_b32_e32 v59, v177
	v_mul_f32_e64 v55, |v59|, s81
	v_exp_f32_e32 v56, v55
	v_cmp_le_f32_e64 s[40:41], 0, v59
	v_add_f32_e32 v60, 1.0, v56
	v_rcp_f32_e32 v55, v60
	s_nop 0
	v_mul_f32_e32 v56, v56, v55
	s_and_saveexec_b64 s[0:1], s[6:7]
	s_xor_b64 s[44:45], exec, s[0:1]
	s_cbranch_execz .LBB0_948
	v_cndmask_b32_e64 v58, v56, v55, s[40:41]
	v_fma_f32 v58, v1, v58, v7
	v_cmp_gt_f32_e64 s[0:1], s92, v58
	s_nop 1
	v_cndmask_b32_e64 v59, 0, 32, s[0:1]
	v_ldexp_f32 v58, v58, v59
	v_log_f32_e32 v58, v58
	s_nop 0
	v_mul_f32_e32 v59, 0x3f317217, v58
	v_fma_f32 v59, v58, s96, -v59
	v_fmac_f32_e32 v59, 0x3377d1cf, v58
	v_fmac_f32_e32 v59, 0x3f317217, v58
	v_cmp_lt_f32_e64 s[42:43], |v58|, s33
	s_nop 1
	v_cndmask_b32_e64 v58, v58, v59, s[42:43]
	v_cndmask_b32_e64 v59, 0, v249, s[0:1]
	v_sub_f32_e32 v58, v58, v59

.LBB0_950:
	s_or_b64 exec, exec, s[44:45]
	v_cndmask_b32_e64 v59, 13, 18, vcc
	v_or_b32_e32 v60, v59, v0
	v_ashrrev_i32_e32 v61, 31, v60
	v_lshlrev_b64 v[60:61], 13, v[60:61]
	v_lshl_add_u64 v[60:61], v[2:3], 0, v[60:61]
	s_waitcnt vmcnt(13)
	v_mov_b32_e32 v62, v178
	v_mul_f32_e64 v59, |v62|, s81
	v_exp_f32_e32 v60, v59
	v_cmp_le_f32_e64 s[42:43], 0, v62
	v_add_f32_e32 v63, 1.0, v60
	v_rcp_f32_e32 v59, v63
	s_nop 0
	v_mul_f32_e32 v60, v60, v59
	s_and_saveexec_b64 s[0:1], s[6:7]
	s_xor_b64 s[46:47], exec, s[0:1]
	s_cbranch_execz .LBB0_952
	v_cndmask_b32_e64 v61, v60, v59, s[42:43]
	v_fma_f32 v61, v1, v61, v7
	v_cmp_gt_f32_e64 s[0:1], s92, v61
	s_nop 1
	v_cndmask_b32_e64 v62, 0, 32, s[0:1]
	v_ldexp_f32 v61, v61, v62
	v_log_f32_e32 v61, v61
	s_nop 0
	v_mul_f32_e32 v62, 0x3f317217, v61
	v_fma_f32 v62, v61, s96, -v62
	v_fmac_f32_e32 v62, 0x3377d1cf, v61
	v_fmac_f32_e32 v62, 0x3f317217, v61
	v_cmp_lt_f32_e64 s[44:45], |v61|, s33
	s_nop 1
	v_cndmask_b32_e64 v61, v61, v62, s[44:45]
	v_cndmask_b32_e64 v62, 0, v249, s[0:1]
	v_sub_f32_e32 v61, v61, v62

.LBB0_954:
	s_or_b64 exec, exec, s[46:47]
	v_cndmask_b32_e64 v62, 12, 19, vcc
	v_or_b32_e32 v62, v62, v0
	v_ashrrev_i32_e32 v63, 31, v62
	v_lshlrev_b64 v[62:63], 13, v[62:63]
	v_lshl_add_u64 v[62:63], v[2:3], 0, v[62:63]
	s_waitcnt vmcnt(12)
	v_mov_b32_e32 v75, v179
	v_mul_f32_e64 v62, |v75|, s81
	v_exp_f32_e32 v63, v62
	v_cmp_le_f32_e64 s[44:45], 0, v75
	v_add_f32_e32 v77, 1.0, v63
	v_rcp_f32_e32 v62, v77
	s_nop 0
	v_mul_f32_e32 v63, v63, v62
	s_and_saveexec_b64 s[0:1], s[6:7]
	s_xor_b64 s[48:49], exec, s[0:1]
	s_cbranch_execz .LBB0_956
	v_cndmask_b32_e64 v65, v63, v62, s[44:45]
	v_fma_f32 v65, v1, v65, v7
	v_cmp_gt_f32_e64 s[0:1], s92, v65
	s_nop 1
	v_cndmask_b32_e64 v75, 0, 32, s[0:1]
	v_ldexp_f32 v65, v65, v75
	v_log_f32_e32 v65, v65
	s_nop 0
	v_mul_f32_e32 v75, 0x3f317217, v65
	v_fma_f32 v75, v65, s96, -v75
	v_fmac_f32_e32 v75, 0x3377d1cf, v65
	v_fmac_f32_e32 v75, 0x3f317217, v65
	v_cmp_lt_f32_e64 s[46:47], |v65|, s33
	s_nop 1
	v_cndmask_b32_e64 v65, v65, v75, s[46:47]
	v_cndmask_b32_e64 v75, 0, v249, s[0:1]
	v_sub_f32_e32 v65, v65, v75

.LBB0_958:
	s_or_b64 exec, exec, s[48:49]
	v_cndmask_b32_e64 v75, 11, 20, vcc
	v_or_b32_e32 v82, v75, v0
	v_ashrrev_i32_e32 v83, 31, v82
	v_lshlrev_b64 v[82:83], 13, v[82:83]
	v_lshl_add_u64 v[82:83], v[2:3], 0, v[82:83]
	s_waitcnt vmcnt(11)
	v_mov_b32_e32 v82, v180
	v_mul_f32_e64 v75, |v82|, s81
	v_exp_f32_e32 v77, v75
	v_cmp_le_f32_e64 s[46:47], 0, v82
	v_add_f32_e32 v83, 1.0, v77
	v_rcp_f32_e32 v75, v83
	s_nop 0
	v_mul_f32_e32 v77, v77, v75
	s_and_saveexec_b64 s[0:1], s[6:7]
	s_xor_b64 s[50:51], exec, s[0:1]
	s_cbranch_execz .LBB0_960
	v_cndmask_b32_e64 v81, v77, v75, s[46:47]
	v_fma_f32 v81, v1, v81, v7
	v_cmp_gt_f32_e64 s[0:1], s92, v81
	s_nop 1
	v_cndmask_b32_e64 v82, 0, 32, s[0:1]
	v_ldexp_f32 v81, v81, v82
	v_log_f32_e32 v81, v81
	s_nop 0
	v_mul_f32_e32 v82, 0x3f317217, v81
	v_fma_f32 v82, v81, s96, -v82
	v_fmac_f32_e32 v82, 0x3377d1cf, v81
	v_fmac_f32_e32 v82, 0x3f317217, v81
	v_cmp_lt_f32_e64 s[48:49], |v81|, s33
	s_nop 1
	v_cndmask_b32_e64 v81, v81, v82, s[48:49]
	v_cndmask_b32_e64 v82, 0, v249, s[0:1]
	v_sub_f32_e32 v81, v81, v82

.LBB0_962:
	s_or_b64 exec, exec, s[50:51]
	v_cndmask_b32_e64 v82, 10, 21, vcc
	v_or_b32_e32 v82, v82, v0
	v_ashrrev_i32_e32 v83, 31, v82
	v_lshlrev_b64 v[82:83], 13, v[82:83]
	v_lshl_add_u64 v[82:83], v[2:3], 0, v[82:83]
	s_waitcnt vmcnt(10)
	v_mov_b32_e32 v85, v181
	v_mul_f32_e64 v82, |v85|, s81
	v_exp_f32_e32 v83, v82
	v_cmp_le_f32_e64 s[48:49], 0, v85
	v_add_f32_e32 v86, 1.0, v83
	v_rcp_f32_e32 v82, v86
	s_nop 0
	v_mul_f32_e32 v83, v83, v82
	s_and_saveexec_b64 s[0:1], s[6:7]
	s_xor_b64 s[52:53], exec, s[0:1]
	s_cbranch_execz .LBB0_964
	v_cndmask_b32_e64 v84, v83, v82, s[48:49]
	v_fma_f32 v84, v1, v84, v7
	v_cmp_gt_f32_e64 s[0:1], s92, v84
	s_nop 1
	v_cndmask_b32_e64 v85, 0, 32, s[0:1]
	v_ldexp_f32 v84, v84, v85
	v_log_f32_e32 v84, v84
	s_nop 0
	v_mul_f32_e32 v85, 0x3f317217, v84
	v_fma_f32 v85, v84, s96, -v85
	v_fmac_f32_e32 v85, 0x3377d1cf, v84
	v_fmac_f32_e32 v85, 0x3f317217, v84
	v_cmp_lt_f32_e64 s[50:51], |v84|, s33
	s_nop 1
	v_cndmask_b32_e64 v84, v84, v85, s[50:51]
	v_cndmask_b32_e64 v85, 0, v249, s[0:1]
	v_sub_f32_e32 v84, v84, v85

.LBB0_966:
	s_or_b64 exec, exec, s[52:53]
	v_cndmask_b32_e64 v85, 9, 22, vcc
	v_or_b32_e32 v86, v85, v0
	v_ashrrev_i32_e32 v87, 31, v86
	v_lshlrev_b64 v[86:87], 13, v[86:87]
	v_lshl_add_u64 v[86:87], v[2:3], 0, v[86:87]
	s_waitcnt vmcnt(9)
	v_mov_b32_e32 v88, v182
	v_mul_f32_e64 v85, |v88|, s81
	v_exp_f32_e32 v86, v85
	v_cmp_le_f32_e64 s[50:51], 0, v88
	v_add_f32_e32 v89, 1.0, v86
	v_rcp_f32_e32 v85, v89
	s_nop 0
	v_mul_f32_e32 v86, v86, v85
	s_and_saveexec_b64 s[0:1], s[6:7]
	s_xor_b64 s[54:55], exec, s[0:1]
	s_cbranch_execz .LBB0_968
	v_cndmask_b32_e64 v87, v86, v85, s[50:51]
	v_fma_f32 v87, v1, v87, v7
	v_cmp_gt_f32_e64 s[0:1], s92, v87
	s_nop 1
	v_cndmask_b32_e64 v88, 0, 32, s[0:1]
	v_ldexp_f32 v87, v87, v88
	v_log_f32_e32 v87, v87
	s_nop 0
	v_mul_f32_e32 v88, 0x3f317217, v87
	v_fma_f32 v88, v87, s96, -v88
	v_fmac_f32_e32 v88, 0x3377d1cf, v87
	v_fmac_f32_e32 v88, 0x3f317217, v87
	v_cmp_lt_f32_e64 s[52:53], |v87|, s33
	s_nop 1
	v_cndmask_b32_e64 v87, v87, v88, s[52:53]
	v_cndmask_b32_e64 v88, 0, v249, s[0:1]
	v_sub_f32_e32 v87, v87, v88

.LBB0_970:
	s_or_b64 exec, exec, s[54:55]
	v_cndmask_b32_e64 v88, 8, 23, vcc
	v_or_b32_e32 v88, v88, v0
	v_ashrrev_i32_e32 v89, 31, v88
	v_lshlrev_b64 v[88:89], 13, v[88:89]
	v_lshl_add_u64 v[88:89], v[2:3], 0, v[88:89]
	s_waitcnt vmcnt(8)
	v_mov_b32_e32 v91, v183
	v_mul_f32_e64 v88, |v91|, s81
	v_exp_f32_e32 v89, v88
	v_cmp_le_f32_e64 s[52:53], 0, v91
	v_add_f32_e32 v92, 1.0, v89
	v_rcp_f32_e32 v88, v92
	s_nop 0
	v_mul_f32_e32 v89, v89, v88
	s_and_saveexec_b64 s[0:1], s[6:7]
	s_xor_b64 s[56:57], exec, s[0:1]
	s_cbranch_execz .LBB0_972
	v_cndmask_b32_e64 v90, v89, v88, s[52:53]
	v_fma_f32 v90, v1, v90, v7
	v_cmp_gt_f32_e64 s[0:1], s92, v90
	s_nop 1
	v_cndmask_b32_e64 v91, 0, 32, s[0:1]
	v_ldexp_f32 v90, v90, v91
	v_log_f32_e32 v90, v90
	s_nop 0
	v_mul_f32_e32 v91, 0x3f317217, v90
	v_fma_f32 v91, v90, s96, -v91
	v_fmac_f32_e32 v91, 0x3377d1cf, v90
	v_fmac_f32_e32 v91, 0x3f317217, v90
	v_cmp_lt_f32_e64 s[54:55], |v90|, s33
	s_nop 1
	v_cndmask_b32_e64 v90, v90, v91, s[54:55]
	v_cndmask_b32_e64 v91, 0, v249, s[0:1]
	v_sub_f32_e32 v90, v90, v91

.LBB0_974:
	s_or_b64 exec, exec, s[56:57]
	v_cndmask_b32_e64 v91, 7, 24, vcc
	v_or_b32_e32 v92, v91, v0
	v_ashrrev_i32_e32 v93, 31, v92
	v_lshlrev_b64 v[92:93], 13, v[92:93]
	v_lshl_add_u64 v[92:93], v[2:3], 0, v[92:93]
	s_waitcnt vmcnt(7)
	v_mov_b32_e32 v94, v184
	v_mul_f32_e64 v91, |v94|, s81
	v_exp_f32_e32 v92, v91
	v_cmp_le_f32_e64 s[54:55], 0, v94
	v_add_f32_e32 v95, 1.0, v92
	v_rcp_f32_e32 v91, v95
	s_nop 0
	v_mul_f32_e32 v92, v92, v91
	s_and_saveexec_b64 s[0:1], s[6:7]
	s_xor_b64 s[58:59], exec, s[0:1]
	s_cbranch_execz .LBB0_976
	v_cndmask_b32_e64 v93, v92, v91, s[54:55]
	v_fma_f32 v93, v1, v93, v7
	v_cmp_gt_f32_e64 s[0:1], s92, v93
	s_nop 1
	v_cndmask_b32_e64 v94, 0, 32, s[0:1]
	v_ldexp_f32 v93, v93, v94
	v_log_f32_e32 v93, v93
	s_nop 0
	v_mul_f32_e32 v94, 0x3f317217, v93
	v_fma_f32 v94, v93, s96, -v94
	v_fmac_f32_e32 v94, 0x3377d1cf, v93
	v_fmac_f32_e32 v94, 0x3f317217, v93
	v_cmp_lt_f32_e64 s[56:57], |v93|, s33
	s_nop 1
	v_cndmask_b32_e64 v93, v93, v94, s[56:57]
	v_cndmask_b32_e64 v94, 0, v249, s[0:1]
	v_sub_f32_e32 v93, v93, v94

.LBB0_978:
	s_or_b64 exec, exec, s[58:59]
	v_cndmask_b32_e64 v94, 6, 25, vcc
	v_or_b32_e32 v94, v94, v0
	v_ashrrev_i32_e32 v95, 31, v94
	v_lshlrev_b64 v[94:95], 13, v[94:95]
	v_lshl_add_u64 v[94:95], v[2:3], 0, v[94:95]
	s_waitcnt vmcnt(6)
	v_mov_b32_e32 v97, v185
	v_mul_f32_e64 v94, |v97|, s81
	v_exp_f32_e32 v95, v94
	v_cmp_le_f32_e64 s[56:57], 0, v97
	v_add_f32_e32 v98, 1.0, v95
	v_rcp_f32_e32 v94, v98
	s_nop 0
	v_mul_f32_e32 v95, v95, v94
	s_and_saveexec_b64 s[0:1], s[6:7]
	s_xor_b64 s[60:61], exec, s[0:1]
	s_cbranch_execz .LBB0_980
	v_cndmask_b32_e64 v96, v95, v94, s[56:57]
	v_fma_f32 v96, v1, v96, v7
	v_cmp_gt_f32_e64 s[0:1], s92, v96
	s_nop 1
	v_cndmask_b32_e64 v97, 0, 32, s[0:1]
	v_ldexp_f32 v96, v96, v97
	v_log_f32_e32 v96, v96
	s_nop 0
	v_mul_f32_e32 v97, 0x3f317217, v96
	v_fma_f32 v97, v96, s96, -v97
	v_fmac_f32_e32 v97, 0x3377d1cf, v96
	v_fmac_f32_e32 v97, 0x3f317217, v96
	v_cmp_lt_f32_e64 s[58:59], |v96|, s33
	s_nop 1
	v_cndmask_b32_e64 v96, v96, v97, s[58:59]
	v_cndmask_b32_e64 v97, 0, v249, s[0:1]
	v_sub_f32_e32 v96, v96, v97

.LBB0_982:
	s_or_b64 exec, exec, s[60:61]
	v_cndmask_b32_e64 v97, 5, 26, vcc
	v_or_b32_e32 v98, v97, v0
	v_ashrrev_i32_e32 v99, 31, v98
	v_lshlrev_b64 v[98:99], 13, v[98:99]
	v_lshl_add_u64 v[98:99], v[2:3], 0, v[98:99]
	s_waitcnt vmcnt(5)
	v_mov_b32_e32 v100, v186
	v_mul_f32_e64 v97, |v100|, s81
	v_exp_f32_e32 v98, v97
	v_cmp_le_f32_e64 s[58:59], 0, v100
	v_add_f32_e32 v101, 1.0, v98
	v_rcp_f32_e32 v97, v101
	s_nop 0
	v_mul_f32_e32 v98, v98, v97
	s_and_saveexec_b64 s[0:1], s[6:7]
	s_xor_b64 s[62:63], exec, s[0:1]
	s_cbranch_execz .LBB0_984
	v_cndmask_b32_e64 v99, v98, v97, s[58:59]
	v_fma_f32 v99, v1, v99, v7
	v_cmp_gt_f32_e64 s[0:1], s92, v99
	s_nop 1
	v_cndmask_b32_e64 v100, 0, 32, s[0:1]
	v_ldexp_f32 v99, v99, v100
	v_log_f32_e32 v99, v99
	s_nop 0
	v_mul_f32_e32 v100, 0x3f317217, v99
	v_fma_f32 v100, v99, s96, -v100
	v_fmac_f32_e32 v100, 0x3377d1cf, v99
	v_fmac_f32_e32 v100, 0x3f317217, v99
	v_cmp_lt_f32_e64 s[60:61], |v99|, s33
	s_nop 1
	v_cndmask_b32_e64 v99, v99, v100, s[60:61]
	v_cndmask_b32_e64 v100, 0, v249, s[0:1]
	v_sub_f32_e32 v99, v99, v100

.LBB0_986:
	s_or_b64 exec, exec, s[62:63]
	v_cndmask_b32_e64 v100, 4, 27, vcc
	v_or_b32_e32 v100, v100, v0
	v_ashrrev_i32_e32 v101, 31, v100
	v_lshlrev_b64 v[100:101], 13, v[100:101]
	v_lshl_add_u64 v[100:101], v[2:3], 0, v[100:101]
	s_waitcnt vmcnt(4)
	v_mov_b32_e32 v103, v187
	v_mul_f32_e64 v100, |v103|, s81
	v_exp_f32_e32 v101, v100
	v_cmp_le_f32_e64 s[60:61], 0, v103
	v_add_f32_e32 v104, 1.0, v101
	v_rcp_f32_e32 v100, v104
	s_nop 0
	v_mul_f32_e32 v101, v101, v100
	s_and_saveexec_b64 s[0:1], s[6:7]
	s_xor_b64 s[64:65], exec, s[0:1]
	s_cbranch_execz .LBB0_988
	v_cndmask_b32_e64 v102, v101, v100, s[60:61]
	v_fma_f32 v102, v1, v102, v7
	v_cmp_gt_f32_e64 s[0:1], s92, v102
	s_nop 1
	v_cndmask_b32_e64 v103, 0, 32, s[0:1]
	v_ldexp_f32 v102, v102, v103
	v_log_f32_e32 v102, v102
	s_nop 0
	v_mul_f32_e32 v103, 0x3f317217, v102
	v_fma_f32 v103, v102, s96, -v103
	v_fmac_f32_e32 v103, 0x3377d1cf, v102
	v_fmac_f32_e32 v103, 0x3f317217, v102
	v_cmp_lt_f32_e64 s[62:63], |v102|, s33
	s_nop 1
	v_cndmask_b32_e64 v102, v102, v103, s[62:63]
	v_cndmask_b32_e64 v103, 0, v249, s[0:1]
	v_sub_f32_e32 v102, v102, v103

.LBB0_990:
	s_or_b64 exec, exec, s[64:65]
	v_cndmask_b32_e64 v103, 3, 28, vcc
	v_or_b32_e32 v104, v103, v0
	v_ashrrev_i32_e32 v105, 31, v104
	v_lshlrev_b64 v[104:105], 13, v[104:105]
	v_lshl_add_u64 v[104:105], v[2:3], 0, v[104:105]
	s_waitcnt vmcnt(3)
	v_mov_b32_e32 v106, v188
	v_mul_f32_e64 v103, |v106|, s81
	v_exp_f32_e32 v104, v103
	v_cmp_le_f32_e64 s[62:63], 0, v106
	v_add_f32_e32 v107, 1.0, v104
	v_rcp_f32_e32 v103, v107
	s_nop 0
	v_mul_f32_e32 v104, v104, v103
	s_and_saveexec_b64 s[0:1], s[6:7]
	s_xor_b64 s[66:67], exec, s[0:1]
	s_cbranch_execz .LBB0_992
	v_cndmask_b32_e64 v105, v104, v103, s[62:63]
	v_fma_f32 v105, v1, v105, v7
	v_cmp_gt_f32_e64 s[0:1], s92, v105
	s_nop 1
	v_cndmask_b32_e64 v106, 0, 32, s[0:1]
	v_ldexp_f32 v105, v105, v106
	v_log_f32_e32 v105, v105
	s_nop 0
	v_mul_f32_e32 v106, 0x3f317217, v105
	v_fma_f32 v106, v105, s96, -v106
	v_fmac_f32_e32 v106, 0x3377d1cf, v105
	v_fmac_f32_e32 v106, 0x3f317217, v105
	v_cmp_lt_f32_e64 s[64:65], |v105|, s33
	s_nop 1
	v_cndmask_b32_e64 v105, v105, v106, s[64:65]
	v_cndmask_b32_e64 v106, 0, v249, s[0:1]
	v_sub_f32_e32 v105, v105, v106

.LBB0_994:
	s_or_b64 exec, exec, s[66:67]
	v_cndmask_b32_e64 v106, 2, 29, vcc
	v_or_b32_e32 v106, v106, v0
	v_ashrrev_i32_e32 v107, 31, v106
	v_lshlrev_b64 v[106:107], 13, v[106:107]
	v_lshl_add_u64 v[106:107], v[2:3], 0, v[106:107]
	s_waitcnt vmcnt(2)
	v_mov_b32_e32 v109, v189
	v_mul_f32_e64 v106, |v109|, s81
	v_exp_f32_e32 v107, v106
	v_cmp_le_f32_e64 s[64:65], 0, v109
	v_add_f32_e32 v110, 1.0, v107
	v_rcp_f32_e32 v106, v110
	s_nop 0
	v_mul_f32_e32 v107, v107, v106
	s_and_saveexec_b64 s[0:1], s[6:7]
	s_xor_b64 s[68:69], exec, s[0:1]
	s_cbranch_execz .LBB0_996
	v_cndmask_b32_e64 v108, v107, v106, s[64:65]
	v_fma_f32 v108, v1, v108, v7
	v_cmp_gt_f32_e64 s[0:1], s92, v108
	s_nop 1
	v_cndmask_b32_e64 v109, 0, 32, s[0:1]
	v_ldexp_f32 v108, v108, v109
	v_log_f32_e32 v108, v108
	s_nop 0
	v_mul_f32_e32 v109, 0x3f317217, v108
	v_fma_f32 v109, v108, s96, -v109
	v_fmac_f32_e32 v109, 0x3377d1cf, v108
	v_fmac_f32_e32 v109, 0x3f317217, v108
	v_cmp_lt_f32_e64 s[66:67], |v108|, s33
	s_nop 1
	v_cndmask_b32_e64 v108, v108, v109, s[66:67]
	v_cndmask_b32_e64 v109, 0, v249, s[0:1]
	v_sub_f32_e32 v108, v108, v109

.LBB0_998:
	s_or_b64 exec, exec, s[68:69]
	v_cndmask_b32_e64 v109, 1, 30, vcc
	v_or_b32_e32 v110, v109, v0
	v_ashrrev_i32_e32 v111, 31, v110
	v_lshlrev_b64 v[110:111], 13, v[110:111]
	v_lshl_add_u64 v[110:111], v[2:3], 0, v[110:111]
	s_waitcnt vmcnt(1)
	v_mov_b32_e32 v112, v190
	v_mul_f32_e64 v109, |v112|, s81
	v_exp_f32_e32 v110, v109
	v_cmp_le_f32_e64 s[66:67], 0, v112
	v_add_f32_e32 v113, 1.0, v110
	v_rcp_f32_e32 v109, v113
	s_nop 0
	v_mul_f32_e32 v110, v110, v109
	s_and_saveexec_b64 s[0:1], s[6:7]
	s_xor_b64 s[78:79], exec, s[0:1]
	s_cbranch_execz .LBB0_1000
	v_cndmask_b32_e64 v111, v110, v109, s[66:67]
	v_fma_f32 v111, v1, v111, v7
	v_cmp_gt_f32_e64 s[0:1], s92, v111
	s_nop 1
	v_cndmask_b32_e64 v112, 0, 32, s[0:1]
	v_ldexp_f32 v111, v111, v112
	v_log_f32_e32 v111, v111
	s_nop 0
	v_mul_f32_e32 v112, 0x3f317217, v111
	v_fma_f32 v112, v111, s96, -v112
	v_fmac_f32_e32 v112, 0x3377d1cf, v111
	v_fmac_f32_e32 v112, 0x3f317217, v111
	v_cmp_lt_f32_e64 s[68:69], |v111|, s33
	s_nop 1
	v_cndmask_b32_e64 v111, v111, v112, s[68:69]
	v_cndmask_b32_e64 v112, 0, v249, s[0:1]
	v_sub_f32_e32 v111, v111, v112

.LBB0_1002:
	s_or_b64 exec, exec, s[78:79]
	v_cndmask_b32_e64 v112, 0, 31, vcc
	v_or_b32_e32 v112, v112, v0
	v_ashrrev_i32_e32 v113, 31, v112
	v_lshlrev_b64 v[112:113], 13, v[112:113]
	v_lshl_add_u64 v[2:3], v[2:3], 0, v[112:113]
	s_waitcnt vmcnt(0)
	v_mov_b32_e32 v112, v191
	v_mul_f32_e64 v0, |v112|, s81
	v_exp_f32_e32 v2, v0
	v_cmp_le_f32_e64 s[68:69], 0, v112
	v_add_f32_e32 v113, 1.0, v2
	v_rcp_f32_e32 v0, v113
	s_nop 0
	v_mul_f32_e32 v2, v2, v0
	s_and_saveexec_b64 s[0:1], s[6:7]
	s_xor_b64 s[78:79], exec, s[0:1]
	s_cbranch_execz .LBB0_1004
	v_cndmask_b32_e64 v3, v2, v0, s[68:69]
	v_fmac_f32_e32 v7, v1, v3
	v_cmp_gt_f32_e64 s[0:1], s92, v7
	s_nop 1
	v_cndmask_b32_e64 v3, 0, 32, s[0:1]
	v_ldexp_f32 v3, v7, v3
	v_log_f32_e32 v3, v3
	s_nop 0
	v_mul_f32_e32 v7, 0x3f317217, v3
	v_fma_f32 v7, v3, s96, -v7
	v_fmac_f32_e32 v7, 0x3377d1cf, v3
	v_fmac_f32_e32 v7, 0x3f317217, v3
	v_cmp_lt_f32_e64 s[6:7], |v3|, s33
	s_nop 1
	v_cndmask_b32_e64 v3, v3, v7, s[6:7]
	v_cndmask_b32_e64 v7, 0, v249, s[0:1]
	v_sub_f32_e32 v3, v3, v7
